# v15 + bf16 MFMA blocks reordered: both k-steps of one accumulator adjacent
# speedup vs baseline: 1.0084x; 1.0084x over previous
.LBB0_422:
	ds_read_b128 v[146:149], v154
	ds_read_b128 v[158:161], v154 offset:1024
	ds_read_b128 v[162:165], v154 offset:2048
	ds_read_b128 v[166:169], v154 offset:3072
	ds_read_b128 v[170:173], v155
	ds_read_b128 v[178:181], v155 offset:1024
	ds_read_b128 v[182:185], v155 offset:2048
	ds_read_b128 v[186:189], v155 offset:3072
	s_add_u32 s30, s28, 0xfc000
	s_addc_u32 s31, s29, 0
	s_cmp_eq_u32 s53, 60
	s_cselect_b32 s36, s21, s30
	s_cselect_b32 s37, s9, s31
	s_cselect_b32 s34, s50, s51
	s_cselect_b32 s35, s19, s52
	s_add_u32 s30, s36, 0x100000
	s_addc_u32 s31, s37, 0
	s_add_i32 m0, s1, 0xc000
	ds_read_b128 v[190:193], v156
	ds_read_b128 v[194:197], v156 offset:1024
	ds_read_b128 v[198:201], v156 offset:2048
	ds_read_b128 v[202:205], v156 offset:3072
	ds_read_b128 v[206:209], v156 offset:4096
	ds_read_b128 v[210:213], v156 offset:5120
	ds_read_b128 v[214:217], v156 offset:6144
	ds_read_b128 v[218:221], v156 offset:7168
	global_load_lds_dwordx4 v138, s[28:29]
	s_add_i32 m0, s1, 0xe000
	s_nop 0
	global_load_lds_dwordx4 v140, s[28:29]
	s_waitcnt vmcnt(8)
	s_waitcnt lgkmcnt(0)
	s_setprio 1
	s_barrier
	v_mfma_f32_16x16x32_bf16 v[126:129], v[146:149], v[190:193], v[126:129]
	v_mfma_f32_16x16x32_bf16 v[126:129], v[158:161], v[194:197], v[126:129]
	v_mfma_f32_16x16x32_bf16 v[122:125], v[162:165], v[190:193], v[122:125]
	v_mfma_f32_16x16x32_bf16 v[122:125], v[166:169], v[194:197], v[122:125]
	v_mfma_f32_16x16x32_bf16 v[110:113], v[146:149], v[198:201], v[110:113]
	v_mfma_f32_16x16x32_bf16 v[110:113], v[158:161], v[202:205], v[110:113]
	v_mfma_f32_16x16x32_bf16 v[106:109], v[162:165], v[198:201], v[106:109]
	v_mfma_f32_16x16x32_bf16 v[106:109], v[166:169], v[202:205], v[106:109]
	v_mfma_f32_16x16x32_bf16 v[94:97], v[146:149], v[206:209], v[94:97]
	v_mfma_f32_16x16x32_bf16 v[94:97], v[158:161], v[210:213], v[94:97]
	v_mfma_f32_16x16x32_bf16 v[90:93], v[162:165], v[206:209], v[90:93]
	v_mfma_f32_16x16x32_bf16 v[90:93], v[166:169], v[210:213], v[90:93]
	v_mfma_f32_16x16x32_bf16 v[78:81], v[146:149], v[214:217], v[78:81]
	v_mfma_f32_16x16x32_bf16 v[78:81], v[158:161], v[218:221], v[78:81]
	v_mfma_f32_16x16x32_bf16 v[74:77], v[162:165], v[214:217], v[74:77]
	v_mfma_f32_16x16x32_bf16 v[74:77], v[166:169], v[218:221], v[74:77]
	s_setprio 0
	s_setprio 1
	v_mfma_f32_16x16x32_bf16 v[118:121], v[170:173], v[190:193], v[118:121]
	v_mfma_f32_16x16x32_bf16 v[118:121], v[178:181], v[194:197], v[118:121]
	v_mfma_f32_16x16x32_bf16 v[114:117], v[182:185], v[190:193], v[114:117]
	v_mfma_f32_16x16x32_bf16 v[114:117], v[186:189], v[194:197], v[114:117]
	v_mfma_f32_16x16x32_bf16 v[102:105], v[170:173], v[198:201], v[102:105]
	v_mfma_f32_16x16x32_bf16 v[102:105], v[178:181], v[202:205], v[102:105]
	v_mfma_f32_16x16x32_bf16 v[98:101], v[182:185], v[198:201], v[98:101]
	v_mfma_f32_16x16x32_bf16 v[98:101], v[186:189], v[202:205], v[98:101]
	v_mfma_f32_16x16x32_bf16 v[86:89], v[170:173], v[206:209], v[86:89]
	v_mfma_f32_16x16x32_bf16 v[86:89], v[178:181], v[210:213], v[86:89]
	v_mfma_f32_16x16x32_bf16 v[82:85], v[182:185], v[206:209], v[82:85]
	v_mfma_f32_16x16x32_bf16 v[82:85], v[186:189], v[210:213], v[82:85]
	v_mfma_f32_16x16x32_bf16 v[70:73], v[170:173], v[214:217], v[70:73]
	v_mfma_f32_16x16x32_bf16 v[70:73], v[178:181], v[218:221], v[70:73]
	v_mfma_f32_16x16x32_bf16 v[66:69], v[182:185], v[214:217], v[66:69]
	v_mfma_f32_16x16x32_bf16 v[66:69], v[186:189], v[218:221], v[66:69]
	s_barrier
	s_setprio 0
	s_add_i32 s54, s48, s0
	s_mov_b32 m0, s54
	ds_read_b128 v[190:193], v156 offset:16384
	ds_read_b128 v[194:197], v156 offset:17408
	ds_read_b128 v[198:201], v156 offset:18432
	ds_read_b128 v[202:205], v156 offset:19456
	ds_read_b128 v[206:209], v156 offset:20480
	ds_read_b128 v[210:213], v156 offset:21504
	ds_read_b128 v[214:217], v156 offset:22528
	ds_read_b128 v[218:221], v156 offset:23552
	global_load_lds_dwordx4 v132, s[34:35]
	s_add_i32 m0, s54, 0x2000
	s_add_u32 s54, s34, 0x4000
	s_addc_u32 s55, s35, 0
	s_add_i32 s56, s49, s0
	global_load_lds_dwordx4 v136, s[34:35]
	s_mov_b32 m0, s56
	s_nop 0
	global_load_lds_dwordx4 v132, s[54:55]
	s_add_i32 m0, s56, 0x2000
	s_nop 0
	global_load_lds_dwordx4 v136, s[54:55]
	s_mov_b32 m0, s1
	s_nop 0
	global_load_lds_dwordx4 v130, s[36:37]
	s_mov_b32 m0, s27
	s_nop 0
	global_load_lds_dwordx4 v134, s[36:37]
	s_waitcnt vmcnt(8)
	s_waitcnt lgkmcnt(0)
	s_setprio 1
	s_barrier
	v_mfma_f32_16x16x32_bf16 v[62:65], v[146:149], v[190:193], v[62:65]
	v_mfma_f32_16x16x32_bf16 v[62:65], v[158:161], v[194:197], v[62:65]
	v_mfma_f32_16x16x32_bf16 v[58:61], v[162:165], v[190:193], v[58:61]
	v_mfma_f32_16x16x32_bf16 v[58:61], v[166:169], v[194:197], v[58:61]
	v_mfma_f32_16x16x32_bf16 v[46:49], v[146:149], v[198:201], v[46:49]
	v_mfma_f32_16x16x32_bf16 v[46:49], v[158:161], v[202:205], v[46:49]
	v_mfma_f32_16x16x32_bf16 v[42:45], v[162:165], v[198:201], v[42:45]
	v_mfma_f32_16x16x32_bf16 v[42:45], v[166:169], v[202:205], v[42:45]
	v_mfma_f32_16x16x32_bf16 v[30:33], v[146:149], v[206:209], v[30:33]
	v_mfma_f32_16x16x32_bf16 v[30:33], v[158:161], v[210:213], v[30:33]
	v_mfma_f32_16x16x32_bf16 v[26:29], v[162:165], v[206:209], v[26:29]
	v_mfma_f32_16x16x32_bf16 v[26:29], v[166:169], v[210:213], v[26:29]
	v_mfma_f32_16x16x32_bf16 v[14:17], v[146:149], v[214:217], v[14:17]
	v_mfma_f32_16x16x32_bf16 v[14:17], v[158:161], v[218:221], v[14:17]
	v_mfma_f32_16x16x32_bf16 v[10:13], v[162:165], v[214:217], v[10:13]
	v_mfma_f32_16x16x32_bf16 v[10:13], v[166:169], v[218:221], v[10:13]
	s_setprio 0
	s_setprio 1
	v_mfma_f32_16x16x32_bf16 v[54:57], v[170:173], v[190:193], v[54:57]
	v_mfma_f32_16x16x32_bf16 v[54:57], v[178:181], v[194:197], v[54:57]
	v_mfma_f32_16x16x32_bf16 v[50:53], v[182:185], v[190:193], v[50:53]
	v_mfma_f32_16x16x32_bf16 v[50:53], v[186:189], v[194:197], v[50:53]
	v_mfma_f32_16x16x32_bf16 v[38:41], v[170:173], v[198:201], v[38:41]
	v_mfma_f32_16x16x32_bf16 v[38:41], v[178:181], v[202:205], v[38:41]
	v_mfma_f32_16x16x32_bf16 v[34:37], v[182:185], v[198:201], v[34:37]
	v_mfma_f32_16x16x32_bf16 v[34:37], v[186:189], v[202:205], v[34:37]
	v_mfma_f32_16x16x32_bf16 v[22:25], v[170:173], v[206:209], v[22:25]
	v_mfma_f32_16x16x32_bf16 v[22:25], v[178:181], v[210:213], v[22:25]
	v_mfma_f32_16x16x32_bf16 v[18:21], v[182:185], v[206:209], v[18:21]
	v_mfma_f32_16x16x32_bf16 v[18:21], v[186:189], v[210:213], v[18:21]
	v_mfma_f32_16x16x32_bf16 v[6:9], v[170:173], v[214:217], v[6:9]
	v_mfma_f32_16x16x32_bf16 v[6:9], v[178:181], v[218:221], v[6:9]
	v_mfma_f32_16x16x32_bf16 v[2:5], v[182:185], v[214:217], v[2:5]
	v_mfma_f32_16x16x32_bf16 v[2:5], v[186:189], v[218:221], v[2:5]
	s_barrier
	s_setprio 0
	s_add_i32 s54, 0, 0x18000
	v_add_u32_e32 v150, s54, v153
	s_add_i32 s55, 0, 0x1c000
	ds_read_b128 v[146:149], v150
	ds_read_b128 v[158:161], v150 offset:1024
	ds_read_b128 v[162:165], v150 offset:2048
	ds_read_b128 v[166:169], v150 offset:3072
	v_add_u32_e32 v150, s55, v153
	ds_read_b128 v[170:173], v150
	ds_read_b128 v[178:181], v150 offset:1024
	ds_read_b128 v[182:185], v150 offset:2048
	ds_read_b128 v[186:189], v150 offset:3072
	s_add_u32 s36, s36, 0x4000
	s_addc_u32 s37, s37, 0
	s_mov_b32 m0, s33
	ds_read_b128 v[190:193], v156 offset:32768
	ds_read_b128 v[194:197], v156 offset:33792
	ds_read_b128 v[198:201], v156 offset:34816
	ds_read_b128 v[202:205], v156 offset:35840
	ds_read_b128 v[206:209], v156 offset:36864
	ds_read_b128 v[210:213], v156 offset:37888
	ds_read_b128 v[214:217], v156 offset:38912
	ds_read_b128 v[218:221], v156 offset:39936
	global_load_lds_dwordx4 v130, s[36:37]
	s_mov_b32 m0, s38
	s_nop 0
	global_load_lds_dwordx4 v134, s[36:37]
	s_waitcnt vmcnt(8)
	s_waitcnt lgkmcnt(0)
	s_setprio 1
	s_barrier
	v_mfma_f32_16x16x32_bf16 v[126:129], v[146:149], v[190:193], v[126:129]
	v_mfma_f32_16x16x32_bf16 v[126:129], v[158:161], v[194:197], v[126:129]
	v_mfma_f32_16x16x32_bf16 v[122:125], v[162:165], v[190:193], v[122:125]
	v_mfma_f32_16x16x32_bf16 v[122:125], v[166:169], v[194:197], v[122:125]
	v_mfma_f32_16x16x32_bf16 v[110:113], v[146:149], v[198:201], v[110:113]
	v_mfma_f32_16x16x32_bf16 v[110:113], v[158:161], v[202:205], v[110:113]
	v_mfma_f32_16x16x32_bf16 v[106:109], v[162:165], v[198:201], v[106:109]
	v_mfma_f32_16x16x32_bf16 v[106:109], v[166:169], v[202:205], v[106:109]
	v_mfma_f32_16x16x32_bf16 v[94:97], v[146:149], v[206:209], v[94:97]
	v_mfma_f32_16x16x32_bf16 v[94:97], v[158:161], v[210:213], v[94:97]
	v_mfma_f32_16x16x32_bf16 v[90:93], v[162:165], v[206:209], v[90:93]
	v_mfma_f32_16x16x32_bf16 v[90:93], v[166:169], v[210:213], v[90:93]
	v_mfma_f32_16x16x32_bf16 v[78:81], v[146:149], v[214:217], v[78:81]
	v_mfma_f32_16x16x32_bf16 v[78:81], v[158:161], v[218:221], v[78:81]
	v_mfma_f32_16x16x32_bf16 v[74:77], v[162:165], v[214:217], v[74:77]
	v_mfma_f32_16x16x32_bf16 v[74:77], v[166:169], v[218:221], v[74:77]
	s_setprio 0
	s_setprio 1
	v_mfma_f32_16x16x32_bf16 v[118:121], v[170:173], v[190:193], v[118:121]
	v_mfma_f32_16x16x32_bf16 v[118:121], v[178:181], v[194:197], v[118:121]
	v_mfma_f32_16x16x32_bf16 v[114:117], v[182:185], v[190:193], v[114:117]
	v_mfma_f32_16x16x32_bf16 v[114:117], v[186:189], v[194:197], v[114:117]
	v_mfma_f32_16x16x32_bf16 v[102:105], v[170:173], v[198:201], v[102:105]
	v_mfma_f32_16x16x32_bf16 v[102:105], v[178:181], v[202:205], v[102:105]
	v_mfma_f32_16x16x32_bf16 v[98:101], v[182:185], v[198:201], v[98:101]
	v_mfma_f32_16x16x32_bf16 v[98:101], v[186:189], v[202:205], v[98:101]
	v_mfma_f32_16x16x32_bf16 v[86:89], v[170:173], v[206:209], v[86:89]
	v_mfma_f32_16x16x32_bf16 v[86:89], v[178:181], v[210:213], v[86:89]
	v_mfma_f32_16x16x32_bf16 v[82:85], v[182:185], v[206:209], v[82:85]
	v_mfma_f32_16x16x32_bf16 v[82:85], v[186:189], v[210:213], v[82:85]
	v_mfma_f32_16x16x32_bf16 v[70:73], v[170:173], v[214:217], v[70:73]
	v_mfma_f32_16x16x32_bf16 v[70:73], v[178:181], v[218:221], v[70:73]
	v_mfma_f32_16x16x32_bf16 v[66:69], v[182:185], v[214:217], v[66:69]
	v_mfma_f32_16x16x32_bf16 v[66:69], v[186:189], v[218:221], v[66:69]
	s_barrier
	s_setprio 0
	s_add_u32 s36, s34, 0x380000
	s_addc_u32 s37, s35, 0
	s_add_i32 s54, s54, s0
	s_mov_b32 m0, s54
	ds_read_b128 v[190:193], v156 offset:49152
	ds_read_b128 v[194:197], v156 offset:50176
	ds_read_b128 v[198:201], v156 offset:51200
	ds_read_b128 v[202:205], v156 offset:52224
	ds_read_b128 v[206:209], v156 offset:53248
	ds_read_b128 v[210:213], v156 offset:54272
	ds_read_b128 v[214:217], v156 offset:55296
	ds_read_b128 v[218:221], v156 offset:56320
	global_load_lds_dwordx4 v132, s[36:37]
	s_add_i32 m0, s54, 0x2000
	s_add_u32 s34, s34, 0x384000
	s_addc_u32 s35, s35, 0
	global_load_lds_dwordx4 v136, s[36:37]
	s_add_i32 s36, s55, s0
	s_mov_b32 m0, s36
	s_nop 0
	global_load_lds_dwordx4 v132, s[34:35]
	s_add_i32 m0, s36, 0x2000
	s_nop 0
	global_load_lds_dwordx4 v136, s[34:35]
	s_mov_b32 m0, s44
	s_nop 0
	global_load_lds_dwordx4 v130, s[30:31]
	s_mov_b32 m0, s45
	s_nop 0
	global_load_lds_dwordx4 v134, s[30:31]
	s_waitcnt vmcnt(8)
	s_waitcnt lgkmcnt(0)
	s_setprio 1
	s_barrier
	v_mfma_f32_16x16x32_bf16 v[62:65], v[146:149], v[190:193], v[62:65]
	v_mfma_f32_16x16x32_bf16 v[62:65], v[158:161], v[194:197], v[62:65]
	v_mfma_f32_16x16x32_bf16 v[58:61], v[162:165], v[190:193], v[58:61]
	v_mfma_f32_16x16x32_bf16 v[58:61], v[166:169], v[194:197], v[58:61]
	v_mfma_f32_16x16x32_bf16 v[46:49], v[146:149], v[198:201], v[46:49]
	v_mfma_f32_16x16x32_bf16 v[46:49], v[158:161], v[202:205], v[46:49]
	v_mfma_f32_16x16x32_bf16 v[42:45], v[162:165], v[198:201], v[42:45]
	v_mfma_f32_16x16x32_bf16 v[42:45], v[166:169], v[202:205], v[42:45]
	v_mfma_f32_16x16x32_bf16 v[30:33], v[146:149], v[206:209], v[30:33]
	v_mfma_f32_16x16x32_bf16 v[30:33], v[158:161], v[210:213], v[30:33]
	v_mfma_f32_16x16x32_bf16 v[26:29], v[162:165], v[206:209], v[26:29]
	v_mfma_f32_16x16x32_bf16 v[26:29], v[166:169], v[210:213], v[26:29]
	v_mfma_f32_16x16x32_bf16 v[14:17], v[146:149], v[214:217], v[14:17]
	v_mfma_f32_16x16x32_bf16 v[14:17], v[158:161], v[218:221], v[14:17]
	v_mfma_f32_16x16x32_bf16 v[10:13], v[162:165], v[214:217], v[10:13]
	v_mfma_f32_16x16x32_bf16 v[10:13], v[166:169], v[218:221], v[10:13]
	s_setprio 0
	s_setprio 1
	v_mfma_f32_16x16x32_bf16 v[54:57], v[170:173], v[190:193], v[54:57]
	v_mfma_f32_16x16x32_bf16 v[54:57], v[178:181], v[194:197], v[54:57]
	v_mfma_f32_16x16x32_bf16 v[50:53], v[182:185], v[190:193], v[50:53]
	v_mfma_f32_16x16x32_bf16 v[50:53], v[186:189], v[194:197], v[50:53]
	v_mfma_f32_16x16x32_bf16 v[38:41], v[170:173], v[198:201], v[38:41]
	v_mfma_f32_16x16x32_bf16 v[38:41], v[178:181], v[202:205], v[38:41]
	v_mfma_f32_16x16x32_bf16 v[34:37], v[182:185], v[198:201], v[34:37]
	v_mfma_f32_16x16x32_bf16 v[34:37], v[186:189], v[202:205], v[34:37]
	v_mfma_f32_16x16x32_bf16 v[22:25], v[170:173], v[206:209], v[22:25]
	v_mfma_f32_16x16x32_bf16 v[22:25], v[178:181], v[210:213], v[22:25]
	v_mfma_f32_16x16x32_bf16 v[18:21], v[182:185], v[206:209], v[18:21]
	v_mfma_f32_16x16x32_bf16 v[18:21], v[186:189], v[210:213], v[18:21]
	v_mfma_f32_16x16x32_bf16 v[6:9], v[170:173], v[214:217], v[6:9]
	v_mfma_f32_16x16x32_bf16 v[6:9], v[178:181], v[218:221], v[6:9]
	v_mfma_f32_16x16x32_bf16 v[2:5], v[182:185], v[214:217], v[2:5]
	v_mfma_f32_16x16x32_bf16 v[2:5], v[186:189], v[218:221], v[2:5]
	s_barrier
	s_setprio 0
	s_add_i32 s53, s53, 2
	s_add_u32 s51, s51, 0x700000
	s_addc_u32 s52, s52, 0
	s_add_u32 s28, s28, 0x200000
	s_addc_u32 s29, s29, 0
	s_cmp_gt_u32 s53, 61
	s_cbranch_scc0 .LBB0_422
	s_and_b64 vcc, exec, s[16:17]
	s_cbranch_vccz .LBB0_425
	s_barrier

.LBB0_501:
	ds_read_b128 v[146:149], v152
	ds_read_b128 v[156:159], v152 offset:1024
	ds_read_b128 v[160:163], v152 offset:2048
	ds_read_b128 v[164:167], v152 offset:3072
	ds_read_b128 v[168:171], v153
	ds_read_b128 v[172:175], v153 offset:1024
	ds_read_b128 v[178:181], v153 offset:2048
	ds_read_b128 v[182:185], v153 offset:3072
	s_add_u32 s26, s10, 0xfc000
	s_addc_u32 s27, s11, 0
	s_cmpk_eq_i32 s47, 0xdc
	s_cselect_b32 s30, s21, s26
	s_cselect_b32 s31, s5, s27
	s_cselect_b32 s28, s44, s45
	s_cselect_b32 s29, s19, s46
	s_add_u32 s26, s30, 0x100000
	s_addc_u32 s27, s31, 0
	s_add_i32 m0, s1, 0xc000
	ds_read_b128 v[186:189], v154
	ds_read_b128 v[190:193], v154 offset:1024
	ds_read_b128 v[194:197], v154 offset:2048
	ds_read_b128 v[198:201], v154 offset:3072
	ds_read_b128 v[202:205], v154 offset:4096
	ds_read_b128 v[206:209], v154 offset:5120
	ds_read_b128 v[210:213], v154 offset:6144
	ds_read_b128 v[214:217], v154 offset:7168
	global_load_lds_dwordx4 v138, s[10:11]
	s_add_i32 m0, s1, 0xe000
	s_nop 0
	global_load_lds_dwordx4 v140, s[10:11]
	s_waitcnt vmcnt(8)
	s_waitcnt lgkmcnt(0)
	s_setprio 1
	s_barrier
	v_mfma_f32_16x16x32_bf16 v[126:129], v[146:149], v[186:189], v[126:129]
	v_mfma_f32_16x16x32_bf16 v[126:129], v[156:159], v[190:193], v[126:129]
	v_mfma_f32_16x16x32_bf16 v[122:125], v[160:163], v[186:189], v[122:125]
	v_mfma_f32_16x16x32_bf16 v[122:125], v[164:167], v[190:193], v[122:125]
	v_mfma_f32_16x16x32_bf16 v[110:113], v[146:149], v[194:197], v[110:113]
	v_mfma_f32_16x16x32_bf16 v[110:113], v[156:159], v[198:201], v[110:113]
	v_mfma_f32_16x16x32_bf16 v[106:109], v[160:163], v[194:197], v[106:109]
	v_mfma_f32_16x16x32_bf16 v[106:109], v[164:167], v[198:201], v[106:109]
	v_mfma_f32_16x16x32_bf16 v[94:97], v[146:149], v[202:205], v[94:97]
	v_mfma_f32_16x16x32_bf16 v[94:97], v[156:159], v[206:209], v[94:97]
	v_mfma_f32_16x16x32_bf16 v[90:93], v[160:163], v[202:205], v[90:93]
	v_mfma_f32_16x16x32_bf16 v[90:93], v[164:167], v[206:209], v[90:93]
	v_mfma_f32_16x16x32_bf16 v[78:81], v[146:149], v[210:213], v[78:81]
	v_mfma_f32_16x16x32_bf16 v[78:81], v[156:159], v[214:217], v[78:81]
	v_mfma_f32_16x16x32_bf16 v[74:77], v[160:163], v[210:213], v[74:77]
	v_mfma_f32_16x16x32_bf16 v[74:77], v[164:167], v[214:217], v[74:77]
	s_setprio 0
	s_setprio 1
	v_mfma_f32_16x16x32_bf16 v[118:121], v[168:171], v[186:189], v[118:121]
	v_mfma_f32_16x16x32_bf16 v[118:121], v[172:175], v[190:193], v[118:121]
	v_mfma_f32_16x16x32_bf16 v[114:117], v[178:181], v[186:189], v[114:117]
	v_mfma_f32_16x16x32_bf16 v[114:117], v[182:185], v[190:193], v[114:117]
	v_mfma_f32_16x16x32_bf16 v[102:105], v[168:171], v[194:197], v[102:105]
	v_mfma_f32_16x16x32_bf16 v[102:105], v[172:175], v[198:201], v[102:105]
	v_mfma_f32_16x16x32_bf16 v[98:101], v[178:181], v[194:197], v[98:101]
	v_mfma_f32_16x16x32_bf16 v[98:101], v[182:185], v[198:201], v[98:101]
	v_mfma_f32_16x16x32_bf16 v[86:89], v[168:171], v[202:205], v[86:89]
	v_mfma_f32_16x16x32_bf16 v[86:89], v[172:175], v[206:209], v[86:89]
	v_mfma_f32_16x16x32_bf16 v[82:85], v[178:181], v[202:205], v[82:85]
	v_mfma_f32_16x16x32_bf16 v[82:85], v[182:185], v[206:209], v[82:85]
	v_mfma_f32_16x16x32_bf16 v[70:73], v[168:171], v[210:213], v[70:73]
	v_mfma_f32_16x16x32_bf16 v[70:73], v[172:175], v[214:217], v[70:73]
	v_mfma_f32_16x16x32_bf16 v[66:69], v[178:181], v[210:213], v[66:69]
	v_mfma_f32_16x16x32_bf16 v[66:69], v[182:185], v[214:217], v[66:69]
	s_barrier
	s_setprio 0
	s_add_i32 s48, s41, s0
	s_mov_b32 m0, s48
	ds_read_b128 v[186:189], v154 offset:16384
	ds_read_b128 v[190:193], v154 offset:17408
	ds_read_b128 v[194:197], v154 offset:18432
	ds_read_b128 v[198:201], v154 offset:19456
	ds_read_b128 v[202:205], v154 offset:20480
	ds_read_b128 v[206:209], v154 offset:21504
	ds_read_b128 v[210:213], v154 offset:22528
	ds_read_b128 v[214:217], v154 offset:23552
	global_load_lds_dwordx4 v132, s[28:29]
	s_add_i32 m0, s48, 0x2000
	s_add_u32 s48, s28, 0x4000
	s_addc_u32 s49, s29, 0
	s_add_i32 s50, s42, s0
	global_load_lds_dwordx4 v136, s[28:29]
	s_mov_b32 m0, s50
	s_nop 0
	global_load_lds_dwordx4 v132, s[48:49]
	s_add_i32 m0, s50, 0x2000
	s_nop 0
	global_load_lds_dwordx4 v136, s[48:49]
	s_mov_b32 m0, s1
	s_nop 0
	global_load_lds_dwordx4 v130, s[30:31]
	s_mov_b32 m0, s33
	s_nop 0
	global_load_lds_dwordx4 v134, s[30:31]
	s_waitcnt vmcnt(8)
	s_waitcnt lgkmcnt(0)
	s_setprio 1
	s_barrier
	v_mfma_f32_16x16x32_bf16 v[62:65], v[146:149], v[186:189], v[62:65]
	v_mfma_f32_16x16x32_bf16 v[62:65], v[156:159], v[190:193], v[62:65]
	v_mfma_f32_16x16x32_bf16 v[58:61], v[160:163], v[186:189], v[58:61]
	v_mfma_f32_16x16x32_bf16 v[58:61], v[164:167], v[190:193], v[58:61]
	v_mfma_f32_16x16x32_bf16 v[46:49], v[146:149], v[194:197], v[46:49]
	v_mfma_f32_16x16x32_bf16 v[46:49], v[156:159], v[198:201], v[46:49]
	v_mfma_f32_16x16x32_bf16 v[42:45], v[160:163], v[194:197], v[42:45]
	v_mfma_f32_16x16x32_bf16 v[42:45], v[164:167], v[198:201], v[42:45]
	v_mfma_f32_16x16x32_bf16 v[30:33], v[146:149], v[202:205], v[30:33]
	v_mfma_f32_16x16x32_bf16 v[30:33], v[156:159], v[206:209], v[30:33]
	v_mfma_f32_16x16x32_bf16 v[26:29], v[160:163], v[202:205], v[26:29]
	v_mfma_f32_16x16x32_bf16 v[26:29], v[164:167], v[206:209], v[26:29]
	v_mfma_f32_16x16x32_bf16 v[14:17], v[146:149], v[210:213], v[14:17]
	v_mfma_f32_16x16x32_bf16 v[14:17], v[156:159], v[214:217], v[14:17]
	v_mfma_f32_16x16x32_bf16 v[10:13], v[160:163], v[210:213], v[10:13]
	v_mfma_f32_16x16x32_bf16 v[10:13], v[164:167], v[214:217], v[10:13]
	s_setprio 0
	s_setprio 1
	v_mfma_f32_16x16x32_bf16 v[54:57], v[168:171], v[186:189], v[54:57]
	v_mfma_f32_16x16x32_bf16 v[54:57], v[172:175], v[190:193], v[54:57]
	v_mfma_f32_16x16x32_bf16 v[50:53], v[178:181], v[186:189], v[50:53]
	v_mfma_f32_16x16x32_bf16 v[50:53], v[182:185], v[190:193], v[50:53]
	v_mfma_f32_16x16x32_bf16 v[38:41], v[168:171], v[194:197], v[38:41]
	v_mfma_f32_16x16x32_bf16 v[38:41], v[172:175], v[198:201], v[38:41]
	v_mfma_f32_16x16x32_bf16 v[34:37], v[178:181], v[194:197], v[34:37]
	v_mfma_f32_16x16x32_bf16 v[34:37], v[182:185], v[198:201], v[34:37]
	v_mfma_f32_16x16x32_bf16 v[22:25], v[168:171], v[202:205], v[22:25]
	v_mfma_f32_16x16x32_bf16 v[22:25], v[172:175], v[206:209], v[22:25]
	v_mfma_f32_16x16x32_bf16 v[18:21], v[178:181], v[202:205], v[18:21]
	v_mfma_f32_16x16x32_bf16 v[18:21], v[182:185], v[206:209], v[18:21]
	v_mfma_f32_16x16x32_bf16 v[6:9], v[168:171], v[210:213], v[6:9]
	v_mfma_f32_16x16x32_bf16 v[6:9], v[172:175], v[214:217], v[6:9]
	v_mfma_f32_16x16x32_bf16 v[2:5], v[178:181], v[210:213], v[2:5]
	v_mfma_f32_16x16x32_bf16 v[2:5], v[182:185], v[214:217], v[2:5]
	s_barrier
	s_setprio 0
	s_add_i32 s48, 0, 0x18000
	s_add_i32 s49, 0, 0x1c000
	v_add_u32_e32 v164, s48, v151
	v_add_u32_e32 v176, s49, v151
	ds_read_b128 v[146:149], v164
	ds_read_b128 v[156:159], v164 offset:1024
	ds_read_b128 v[160:163], v164 offset:2048
	ds_read_b128 v[164:167], v164 offset:3072
	ds_read_b128 v[168:171], v176
	ds_read_b128 v[172:175], v176 offset:1024
	ds_read_b128 v[178:181], v176 offset:2048
	ds_read_b128 v[182:185], v176 offset:3072
	s_add_u32 s30, s30, 0x4000
	s_addc_u32 s31, s31, 0
	s_mov_b32 m0, s34
	ds_read_b128 v[186:189], v154 offset:32768
	ds_read_b128 v[190:193], v154 offset:33792
	ds_read_b128 v[194:197], v154 offset:34816
	ds_read_b128 v[198:201], v154 offset:35840
	ds_read_b128 v[202:205], v154 offset:36864
	ds_read_b128 v[206:209], v154 offset:37888
	ds_read_b128 v[210:213], v154 offset:38912
	ds_read_b128 v[214:217], v154 offset:39936
	global_load_lds_dwordx4 v130, s[30:31]
	s_mov_b32 m0, s35
	s_nop 0
	global_load_lds_dwordx4 v134, s[30:31]
	s_waitcnt vmcnt(8)
	s_waitcnt lgkmcnt(0)
	s_setprio 1
	s_barrier
	v_mfma_f32_16x16x32_bf16 v[126:129], v[146:149], v[186:189], v[126:129]
	v_mfma_f32_16x16x32_bf16 v[126:129], v[156:159], v[190:193], v[126:129]
	v_mfma_f32_16x16x32_bf16 v[122:125], v[160:163], v[186:189], v[122:125]
	v_mfma_f32_16x16x32_bf16 v[122:125], v[164:167], v[190:193], v[122:125]
	v_mfma_f32_16x16x32_bf16 v[110:113], v[146:149], v[194:197], v[110:113]
	v_mfma_f32_16x16x32_bf16 v[110:113], v[156:159], v[198:201], v[110:113]
	v_mfma_f32_16x16x32_bf16 v[106:109], v[160:163], v[194:197], v[106:109]
	v_mfma_f32_16x16x32_bf16 v[106:109], v[164:167], v[198:201], v[106:109]
	v_mfma_f32_16x16x32_bf16 v[94:97], v[146:149], v[202:205], v[94:97]
	v_mfma_f32_16x16x32_bf16 v[94:97], v[156:159], v[206:209], v[94:97]
	v_mfma_f32_16x16x32_bf16 v[90:93], v[160:163], v[202:205], v[90:93]
	v_mfma_f32_16x16x32_bf16 v[90:93], v[164:167], v[206:209], v[90:93]
	v_mfma_f32_16x16x32_bf16 v[78:81], v[146:149], v[210:213], v[78:81]
	v_mfma_f32_16x16x32_bf16 v[78:81], v[156:159], v[214:217], v[78:81]
	v_mfma_f32_16x16x32_bf16 v[74:77], v[160:163], v[210:213], v[74:77]
	v_mfma_f32_16x16x32_bf16 v[74:77], v[164:167], v[214:217], v[74:77]
	s_setprio 0
	s_setprio 1
	v_mfma_f32_16x16x32_bf16 v[118:121], v[168:171], v[186:189], v[118:121]
	v_mfma_f32_16x16x32_bf16 v[118:121], v[172:175], v[190:193], v[118:121]
	v_mfma_f32_16x16x32_bf16 v[114:117], v[178:181], v[186:189], v[114:117]
	v_mfma_f32_16x16x32_bf16 v[114:117], v[182:185], v[190:193], v[114:117]
	v_mfma_f32_16x16x32_bf16 v[102:105], v[168:171], v[194:197], v[102:105]
	v_mfma_f32_16x16x32_bf16 v[102:105], v[172:175], v[198:201], v[102:105]
	v_mfma_f32_16x16x32_bf16 v[98:101], v[178:181], v[194:197], v[98:101]
	v_mfma_f32_16x16x32_bf16 v[98:101], v[182:185], v[198:201], v[98:101]
	v_mfma_f32_16x16x32_bf16 v[86:89], v[168:171], v[202:205], v[86:89]
	v_mfma_f32_16x16x32_bf16 v[86:89], v[172:175], v[206:209], v[86:89]
	v_mfma_f32_16x16x32_bf16 v[82:85], v[178:181], v[202:205], v[82:85]
	v_mfma_f32_16x16x32_bf16 v[82:85], v[182:185], v[206:209], v[82:85]
	v_mfma_f32_16x16x32_bf16 v[70:73], v[168:171], v[210:213], v[70:73]
	v_mfma_f32_16x16x32_bf16 v[70:73], v[172:175], v[214:217], v[70:73]
	v_mfma_f32_16x16x32_bf16 v[66:69], v[178:181], v[210:213], v[66:69]
	v_mfma_f32_16x16x32_bf16 v[66:69], v[182:185], v[214:217], v[66:69]
	s_barrier
	s_setprio 0
	s_add_u32 s30, s28, 0x80000
	s_addc_u32 s31, s29, 0
	s_add_i32 s48, s48, s0
	s_mov_b32 m0, s48
	ds_read_b128 v[186:189], v154 offset:49152
	ds_read_b128 v[190:193], v154 offset:50176
	ds_read_b128 v[194:197], v154 offset:51200
	ds_read_b128 v[198:201], v154 offset:52224
	ds_read_b128 v[202:205], v154 offset:53248
	ds_read_b128 v[206:209], v154 offset:54272
	ds_read_b128 v[210:213], v154 offset:55296
	ds_read_b128 v[214:217], v154 offset:56320
	global_load_lds_dwordx4 v132, s[30:31]
	s_add_i32 m0, s48, 0x2000
	s_add_u32 s28, s28, 0x84000
	s_addc_u32 s29, s29, 0
	global_load_lds_dwordx4 v136, s[30:31]
	s_add_i32 s30, s49, s0
	s_mov_b32 m0, s30
	s_nop 0
	global_load_lds_dwordx4 v132, s[28:29]
	s_add_i32 m0, s30, 0x2000
	s_nop 0
	global_load_lds_dwordx4 v136, s[28:29]
	s_mov_b32 m0, s39
	s_nop 0
	global_load_lds_dwordx4 v130, s[26:27]
	s_mov_b32 m0, s40
	s_nop 0
	global_load_lds_dwordx4 v134, s[26:27]
	s_waitcnt vmcnt(8)
	s_waitcnt lgkmcnt(0)
	s_setprio 1
	s_barrier
	v_mfma_f32_16x16x32_bf16 v[62:65], v[146:149], v[186:189], v[62:65]
	v_mfma_f32_16x16x32_bf16 v[62:65], v[156:159], v[190:193], v[62:65]
	v_mfma_f32_16x16x32_bf16 v[58:61], v[160:163], v[186:189], v[58:61]
	v_mfma_f32_16x16x32_bf16 v[58:61], v[164:167], v[190:193], v[58:61]
	v_mfma_f32_16x16x32_bf16 v[46:49], v[146:149], v[194:197], v[46:49]
	v_mfma_f32_16x16x32_bf16 v[46:49], v[156:159], v[198:201], v[46:49]
	v_mfma_f32_16x16x32_bf16 v[42:45], v[160:163], v[194:197], v[42:45]
	v_mfma_f32_16x16x32_bf16 v[42:45], v[164:167], v[198:201], v[42:45]
	v_mfma_f32_16x16x32_bf16 v[30:33], v[146:149], v[202:205], v[30:33]
	v_mfma_f32_16x16x32_bf16 v[30:33], v[156:159], v[206:209], v[30:33]
	v_mfma_f32_16x16x32_bf16 v[26:29], v[160:163], v[202:205], v[26:29]
	v_mfma_f32_16x16x32_bf16 v[26:29], v[164:167], v[206:209], v[26:29]
	v_mfma_f32_16x16x32_bf16 v[14:17], v[146:149], v[210:213], v[14:17]
	v_mfma_f32_16x16x32_bf16 v[14:17], v[156:159], v[214:217], v[14:17]
	v_mfma_f32_16x16x32_bf16 v[10:13], v[160:163], v[210:213], v[10:13]
	v_mfma_f32_16x16x32_bf16 v[10:13], v[164:167], v[214:217], v[10:13]
	s_setprio 0
	s_setprio 1
	v_mfma_f32_16x16x32_bf16 v[54:57], v[168:171], v[186:189], v[54:57]
	v_mfma_f32_16x16x32_bf16 v[54:57], v[172:175], v[190:193], v[54:57]
	v_mfma_f32_16x16x32_bf16 v[50:53], v[178:181], v[186:189], v[50:53]
	v_mfma_f32_16x16x32_bf16 v[50:53], v[182:185], v[190:193], v[50:53]
	v_mfma_f32_16x16x32_bf16 v[38:41], v[168:171], v[194:197], v[38:41]
	v_mfma_f32_16x16x32_bf16 v[38:41], v[172:175], v[198:201], v[38:41]
	v_mfma_f32_16x16x32_bf16 v[34:37], v[178:181], v[194:197], v[34:37]
	v_mfma_f32_16x16x32_bf16 v[34:37], v[182:185], v[198:201], v[34:37]
	v_mfma_f32_16x16x32_bf16 v[22:25], v[168:171], v[202:205], v[22:25]
	v_mfma_f32_16x16x32_bf16 v[22:25], v[172:175], v[206:209], v[22:25]
	v_mfma_f32_16x16x32_bf16 v[18:21], v[178:181], v[202:205], v[18:21]
	v_mfma_f32_16x16x32_bf16 v[18:21], v[182:185], v[206:209], v[18:21]
	v_mfma_f32_16x16x32_bf16 v[6:9], v[168:171], v[210:213], v[6:9]
	v_mfma_f32_16x16x32_bf16 v[6:9], v[172:175], v[214:217], v[6:9]
	v_mfma_f32_16x16x32_bf16 v[2:5], v[178:181], v[210:213], v[2:5]
	v_mfma_f32_16x16x32_bf16 v[2:5], v[182:185], v[214:217], v[2:5]
	s_barrier
	s_setprio 0
	s_add_i32 s47, s47, 2
	s_add_u32 s45, s45, 0x100000
	s_addc_u32 s46, s46, 0
	s_add_u32 s10, s10, 0x200000
	s_addc_u32 s11, s11, 0
	s_cmpk_gt_u32 s47, 0xdd
	s_cbranch_scc0 .LBB0_501
	s_and_b64 vcc, exec, s[16:17]
	s_cbranch_vccz .LBB0_504
	s_barrier

.LBB0_801:
	ds_read_b128 v[130:133], v179
	ds_read_b128 v[134:137], v179 offset:1024
	ds_read_b128 v[156:159], v179 offset:2048
	ds_read_b128 v[160:163], v179 offset:3072
	ds_read_b128 v[164:167], v180
	ds_read_b128 v[168:171], v180 offset:1024
	ds_read_b128 v[172:175], v180 offset:2048
	ds_read_b128 v[186:189], v180 offset:3072
	s_add_u32 s26, s12, 0xfc000
	s_addc_u32 s27, s13, 0
	s_cmp_eq_u32 s47, 60
	s_cselect_b32 s30, s5, s26
	s_cselect_b32 s31, s3, s27
	s_cselect_b32 s28, s21, s45
	s_cselect_b32 s29, s19, s46
	s_add_u32 s26, s30, 0x100000
	s_addc_u32 s27, s31, 0
	s_add_i32 m0, s1, 0xc000
	ds_read_b128 v[190:193], v181
	ds_read_b128 v[194:197], v181 offset:1024
	ds_read_b128 v[198:201], v181 offset:2048
	ds_read_b128 v[202:205], v181 offset:3072
	ds_read_b128 v[206:209], v181 offset:4096
	ds_read_b128 v[210:213], v181 offset:5120
	ds_read_b128 v[214:217], v181 offset:6144
	ds_read_b128 v[218:221], v181 offset:7168
	global_load_lds_dwordx4 v148, s[12:13]
	s_add_i32 m0, s1, 0xe000
	s_nop 0
	global_load_lds_dwordx4 v150, s[12:13]
	s_waitcnt vmcnt(8)
	s_waitcnt lgkmcnt(0)
	s_setprio 1
	s_barrier
	v_mfma_f32_16x16x32_bf16 v[126:129], v[130:133], v[190:193], v[126:129]
	v_mfma_f32_16x16x32_bf16 v[126:129], v[134:137], v[194:197], v[126:129]
	v_mfma_f32_16x16x32_bf16 v[122:125], v[156:159], v[190:193], v[122:125]
	v_mfma_f32_16x16x32_bf16 v[122:125], v[160:163], v[194:197], v[122:125]
	v_mfma_f32_16x16x32_bf16 v[110:113], v[130:133], v[198:201], v[110:113]
	v_mfma_f32_16x16x32_bf16 v[110:113], v[134:137], v[202:205], v[110:113]
	v_mfma_f32_16x16x32_bf16 v[106:109], v[156:159], v[198:201], v[106:109]
	v_mfma_f32_16x16x32_bf16 v[106:109], v[160:163], v[202:205], v[106:109]
	v_mfma_f32_16x16x32_bf16 v[94:97], v[130:133], v[206:209], v[94:97]
	v_mfma_f32_16x16x32_bf16 v[94:97], v[134:137], v[210:213], v[94:97]
	v_mfma_f32_16x16x32_bf16 v[90:93], v[156:159], v[206:209], v[90:93]
	v_mfma_f32_16x16x32_bf16 v[90:93], v[160:163], v[210:213], v[90:93]
	v_mfma_f32_16x16x32_bf16 v[78:81], v[130:133], v[214:217], v[78:81]
	v_mfma_f32_16x16x32_bf16 v[78:81], v[134:137], v[218:221], v[78:81]
	v_mfma_f32_16x16x32_bf16 v[74:77], v[156:159], v[214:217], v[74:77]
	v_mfma_f32_16x16x32_bf16 v[74:77], v[160:163], v[218:221], v[74:77]
	s_setprio 0
	s_setprio 1
	v_mfma_f32_16x16x32_bf16 v[118:121], v[164:167], v[190:193], v[118:121]
	v_mfma_f32_16x16x32_bf16 v[118:121], v[168:171], v[194:197], v[118:121]
	v_mfma_f32_16x16x32_bf16 v[114:117], v[172:175], v[190:193], v[114:117]
	v_mfma_f32_16x16x32_bf16 v[114:117], v[186:189], v[194:197], v[114:117]
	v_mfma_f32_16x16x32_bf16 v[102:105], v[164:167], v[198:201], v[102:105]
	v_mfma_f32_16x16x32_bf16 v[102:105], v[168:171], v[202:205], v[102:105]
	v_mfma_f32_16x16x32_bf16 v[98:101], v[172:175], v[198:201], v[98:101]
	v_mfma_f32_16x16x32_bf16 v[98:101], v[186:189], v[202:205], v[98:101]
	v_mfma_f32_16x16x32_bf16 v[86:89], v[164:167], v[206:209], v[86:89]
	v_mfma_f32_16x16x32_bf16 v[86:89], v[168:171], v[210:213], v[86:89]
	v_mfma_f32_16x16x32_bf16 v[82:85], v[172:175], v[206:209], v[82:85]
	v_mfma_f32_16x16x32_bf16 v[82:85], v[186:189], v[210:213], v[82:85]
	v_mfma_f32_16x16x32_bf16 v[70:73], v[164:167], v[214:217], v[70:73]
	v_mfma_f32_16x16x32_bf16 v[70:73], v[168:171], v[218:221], v[70:73]
	v_mfma_f32_16x16x32_bf16 v[66:69], v[172:175], v[214:217], v[66:69]
	v_mfma_f32_16x16x32_bf16 v[66:69], v[186:189], v[218:221], v[66:69]
	s_barrier
	s_setprio 0
	s_add_i32 s48, s42, s0
	s_mov_b32 m0, s48
	ds_read_b128 v[190:193], v181 offset:16384
	ds_read_b128 v[194:197], v181 offset:17408
	ds_read_b128 v[198:201], v181 offset:18432
	ds_read_b128 v[202:205], v181 offset:19456
	ds_read_b128 v[206:209], v181 offset:20480
	ds_read_b128 v[210:213], v181 offset:21504
	ds_read_b128 v[214:217], v181 offset:22528
	ds_read_b128 v[218:221], v181 offset:23552
	global_load_lds_dwordx4 v140, s[28:29]
	s_add_i32 m0, s48, 0x2000
	s_add_u32 s48, s28, 0x4000
	s_addc_u32 s49, s29, 0
	s_add_i32 s50, s43, s0
	global_load_lds_dwordx4 v144, s[28:29]
	s_mov_b32 m0, s50
	s_nop 0
	global_load_lds_dwordx4 v140, s[48:49]
	s_add_i32 m0, s50, 0x2000
	s_nop 0
	global_load_lds_dwordx4 v144, s[48:49]
	s_mov_b32 m0, s1
	s_nop 0
	global_load_lds_dwordx4 v138, s[30:31]
	s_mov_b32 m0, s33
	s_nop 0
	global_load_lds_dwordx4 v142, s[30:31]
	s_waitcnt vmcnt(8)
	s_waitcnt lgkmcnt(0)
	s_setprio 1
	s_barrier
	v_mfma_f32_16x16x32_bf16 v[62:65], v[130:133], v[190:193], v[62:65]
	v_mfma_f32_16x16x32_bf16 v[62:65], v[134:137], v[194:197], v[62:65]
	v_mfma_f32_16x16x32_bf16 v[58:61], v[156:159], v[190:193], v[58:61]
	v_mfma_f32_16x16x32_bf16 v[58:61], v[160:163], v[194:197], v[58:61]
	v_mfma_f32_16x16x32_bf16 v[46:49], v[130:133], v[198:201], v[46:49]
	v_mfma_f32_16x16x32_bf16 v[46:49], v[134:137], v[202:205], v[46:49]
	v_mfma_f32_16x16x32_bf16 v[42:45], v[156:159], v[198:201], v[42:45]
	v_mfma_f32_16x16x32_bf16 v[42:45], v[160:163], v[202:205], v[42:45]
	v_mfma_f32_16x16x32_bf16 v[30:33], v[130:133], v[206:209], v[30:33]
	v_mfma_f32_16x16x32_bf16 v[30:33], v[134:137], v[210:213], v[30:33]
	v_mfma_f32_16x16x32_bf16 v[26:29], v[156:159], v[206:209], v[26:29]
	v_mfma_f32_16x16x32_bf16 v[26:29], v[160:163], v[210:213], v[26:29]
	v_mfma_f32_16x16x32_bf16 v[14:17], v[130:133], v[214:217], v[14:17]
	v_mfma_f32_16x16x32_bf16 v[14:17], v[134:137], v[218:221], v[14:17]
	v_mfma_f32_16x16x32_bf16 v[10:13], v[156:159], v[214:217], v[10:13]
	v_mfma_f32_16x16x32_bf16 v[10:13], v[160:163], v[218:221], v[10:13]
	s_setprio 0
	s_setprio 1
	v_mfma_f32_16x16x32_bf16 v[54:57], v[164:167], v[190:193], v[54:57]
	v_mfma_f32_16x16x32_bf16 v[54:57], v[168:171], v[194:197], v[54:57]
	v_mfma_f32_16x16x32_bf16 v[50:53], v[172:175], v[190:193], v[50:53]
	v_mfma_f32_16x16x32_bf16 v[50:53], v[186:189], v[194:197], v[50:53]
	v_mfma_f32_16x16x32_bf16 v[38:41], v[164:167], v[198:201], v[38:41]
	v_mfma_f32_16x16x32_bf16 v[38:41], v[168:171], v[202:205], v[38:41]
	v_mfma_f32_16x16x32_bf16 v[34:37], v[172:175], v[198:201], v[34:37]
	v_mfma_f32_16x16x32_bf16 v[34:37], v[186:189], v[202:205], v[34:37]
	v_mfma_f32_16x16x32_bf16 v[22:25], v[164:167], v[206:209], v[22:25]
	v_mfma_f32_16x16x32_bf16 v[22:25], v[168:171], v[210:213], v[22:25]
	v_mfma_f32_16x16x32_bf16 v[18:21], v[172:175], v[206:209], v[18:21]
	v_mfma_f32_16x16x32_bf16 v[18:21], v[186:189], v[210:213], v[18:21]
	v_mfma_f32_16x16x32_bf16 v[6:9], v[164:167], v[214:217], v[6:9]
	v_mfma_f32_16x16x32_bf16 v[6:9], v[168:171], v[218:221], v[6:9]
	v_mfma_f32_16x16x32_bf16 v[2:5], v[172:175], v[214:217], v[2:5]
	v_mfma_f32_16x16x32_bf16 v[2:5], v[186:189], v[218:221], v[2:5]
	s_barrier
	s_setprio 0
	s_add_i32 s48, 0, 0x18000
	v_add_u32_e32 v146, s48, v178
	s_add_i32 s49, 0, 0x1c000
	ds_read_b128 v[130:133], v146
	ds_read_b128 v[134:137], v146 offset:1024
	ds_read_b128 v[156:159], v146 offset:2048
	ds_read_b128 v[160:163], v146 offset:3072
	v_add_u32_e32 v146, s49, v178
	ds_read_b128 v[164:167], v146
	ds_read_b128 v[168:171], v146 offset:1024
	ds_read_b128 v[172:175], v146 offset:2048
	ds_read_b128 v[186:189], v146 offset:3072
	s_add_u32 s30, s30, 0x4000
	s_addc_u32 s31, s31, 0
	s_mov_b32 m0, s34
	ds_read_b128 v[190:193], v181 offset:32768
	ds_read_b128 v[194:197], v181 offset:33792
	ds_read_b128 v[198:201], v181 offset:34816
	ds_read_b128 v[202:205], v181 offset:35840
	ds_read_b128 v[206:209], v181 offset:36864
	ds_read_b128 v[210:213], v181 offset:37888
	ds_read_b128 v[214:217], v181 offset:38912
	ds_read_b128 v[218:221], v181 offset:39936
	global_load_lds_dwordx4 v138, s[30:31]
	s_mov_b32 m0, s35
	s_nop 0
	global_load_lds_dwordx4 v142, s[30:31]
	s_waitcnt vmcnt(8)
	s_waitcnt lgkmcnt(0)
	s_setprio 1
	s_barrier
	v_mfma_f32_16x16x32_bf16 v[126:129], v[130:133], v[190:193], v[126:129]
	v_mfma_f32_16x16x32_bf16 v[126:129], v[134:137], v[194:197], v[126:129]
	v_mfma_f32_16x16x32_bf16 v[122:125], v[156:159], v[190:193], v[122:125]
	v_mfma_f32_16x16x32_bf16 v[122:125], v[160:163], v[194:197], v[122:125]
	v_mfma_f32_16x16x32_bf16 v[110:113], v[130:133], v[198:201], v[110:113]
	v_mfma_f32_16x16x32_bf16 v[110:113], v[134:137], v[202:205], v[110:113]
	v_mfma_f32_16x16x32_bf16 v[106:109], v[156:159], v[198:201], v[106:109]
	v_mfma_f32_16x16x32_bf16 v[106:109], v[160:163], v[202:205], v[106:109]
	v_mfma_f32_16x16x32_bf16 v[94:97], v[130:133], v[206:209], v[94:97]
	v_mfma_f32_16x16x32_bf16 v[94:97], v[134:137], v[210:213], v[94:97]
	v_mfma_f32_16x16x32_bf16 v[90:93], v[156:159], v[206:209], v[90:93]
	v_mfma_f32_16x16x32_bf16 v[90:93], v[160:163], v[210:213], v[90:93]
	v_mfma_f32_16x16x32_bf16 v[78:81], v[130:133], v[214:217], v[78:81]
	v_mfma_f32_16x16x32_bf16 v[78:81], v[134:137], v[218:221], v[78:81]
	v_mfma_f32_16x16x32_bf16 v[74:77], v[156:159], v[214:217], v[74:77]
	v_mfma_f32_16x16x32_bf16 v[74:77], v[160:163], v[218:221], v[74:77]
	s_setprio 0
	s_setprio 1
	v_mfma_f32_16x16x32_bf16 v[118:121], v[164:167], v[190:193], v[118:121]
	v_mfma_f32_16x16x32_bf16 v[118:121], v[168:171], v[194:197], v[118:121]
	v_mfma_f32_16x16x32_bf16 v[114:117], v[172:175], v[190:193], v[114:117]
	v_mfma_f32_16x16x32_bf16 v[114:117], v[186:189], v[194:197], v[114:117]
	v_mfma_f32_16x16x32_bf16 v[102:105], v[164:167], v[198:201], v[102:105]
	v_mfma_f32_16x16x32_bf16 v[102:105], v[168:171], v[202:205], v[102:105]
	v_mfma_f32_16x16x32_bf16 v[98:101], v[172:175], v[198:201], v[98:101]
	v_mfma_f32_16x16x32_bf16 v[98:101], v[186:189], v[202:205], v[98:101]
	v_mfma_f32_16x16x32_bf16 v[86:89], v[164:167], v[206:209], v[86:89]
	v_mfma_f32_16x16x32_bf16 v[86:89], v[168:171], v[210:213], v[86:89]
	v_mfma_f32_16x16x32_bf16 v[82:85], v[172:175], v[206:209], v[82:85]
	v_mfma_f32_16x16x32_bf16 v[82:85], v[186:189], v[210:213], v[82:85]
	v_mfma_f32_16x16x32_bf16 v[70:73], v[164:167], v[214:217], v[70:73]
	v_mfma_f32_16x16x32_bf16 v[70:73], v[168:171], v[218:221], v[70:73]
	v_mfma_f32_16x16x32_bf16 v[66:69], v[172:175], v[214:217], v[66:69]
	v_mfma_f32_16x16x32_bf16 v[66:69], v[186:189], v[218:221], v[66:69]
	s_barrier
	s_setprio 0
	s_add_u32 s30, s28, 0x180000
	s_addc_u32 s31, s29, 0
	s_add_i32 s48, s48, s0
	s_mov_b32 m0, s48
	ds_read_b128 v[190:193], v181 offset:49152
	ds_read_b128 v[194:197], v181 offset:50176
	ds_read_b128 v[198:201], v181 offset:51200
	ds_read_b128 v[202:205], v181 offset:52224
	ds_read_b128 v[206:209], v181 offset:53248
	ds_read_b128 v[210:213], v181 offset:54272
	ds_read_b128 v[214:217], v181 offset:55296
	ds_read_b128 v[218:221], v181 offset:56320
	global_load_lds_dwordx4 v140, s[30:31]
	s_add_i32 m0, s48, 0x2000
	s_add_u32 s28, s28, 0x184000
	s_addc_u32 s29, s29, 0
	global_load_lds_dwordx4 v144, s[30:31]
	s_add_i32 s30, s49, s0
	s_mov_b32 m0, s30
	s_nop 0
	global_load_lds_dwordx4 v140, s[28:29]
	s_add_i32 m0, s30, 0x2000
	s_nop 0
	global_load_lds_dwordx4 v144, s[28:29]
	s_mov_b32 m0, s38
	s_nop 0
	global_load_lds_dwordx4 v138, s[26:27]
	s_mov_b32 m0, s39
	s_nop 0
	global_load_lds_dwordx4 v142, s[26:27]
	s_waitcnt vmcnt(8)
	s_waitcnt lgkmcnt(0)
	s_setprio 1
	s_barrier
	v_mfma_f32_16x16x32_bf16 v[62:65], v[130:133], v[190:193], v[62:65]
	v_mfma_f32_16x16x32_bf16 v[62:65], v[134:137], v[194:197], v[62:65]
	v_mfma_f32_16x16x32_bf16 v[58:61], v[156:159], v[190:193], v[58:61]
	v_mfma_f32_16x16x32_bf16 v[58:61], v[160:163], v[194:197], v[58:61]
	v_mfma_f32_16x16x32_bf16 v[46:49], v[130:133], v[198:201], v[46:49]
	v_mfma_f32_16x16x32_bf16 v[46:49], v[134:137], v[202:205], v[46:49]
	v_mfma_f32_16x16x32_bf16 v[42:45], v[156:159], v[198:201], v[42:45]
	v_mfma_f32_16x16x32_bf16 v[42:45], v[160:163], v[202:205], v[42:45]
	v_mfma_f32_16x16x32_bf16 v[30:33], v[130:133], v[206:209], v[30:33]
	v_mfma_f32_16x16x32_bf16 v[30:33], v[134:137], v[210:213], v[30:33]
	v_mfma_f32_16x16x32_bf16 v[26:29], v[156:159], v[206:209], v[26:29]
	v_mfma_f32_16x16x32_bf16 v[26:29], v[160:163], v[210:213], v[26:29]
	v_mfma_f32_16x16x32_bf16 v[14:17], v[130:133], v[214:217], v[14:17]
	v_mfma_f32_16x16x32_bf16 v[14:17], v[134:137], v[218:221], v[14:17]
	v_mfma_f32_16x16x32_bf16 v[10:13], v[156:159], v[214:217], v[10:13]
	v_mfma_f32_16x16x32_bf16 v[10:13], v[160:163], v[218:221], v[10:13]
	s_setprio 0
	s_setprio 1
	v_mfma_f32_16x16x32_bf16 v[54:57], v[164:167], v[190:193], v[54:57]
	v_mfma_f32_16x16x32_bf16 v[54:57], v[168:171], v[194:197], v[54:57]
	v_mfma_f32_16x16x32_bf16 v[50:53], v[172:175], v[190:193], v[50:53]
	v_mfma_f32_16x16x32_bf16 v[50:53], v[186:189], v[194:197], v[50:53]
	v_mfma_f32_16x16x32_bf16 v[38:41], v[164:167], v[198:201], v[38:41]
	v_mfma_f32_16x16x32_bf16 v[38:41], v[168:171], v[202:205], v[38:41]
	v_mfma_f32_16x16x32_bf16 v[34:37], v[172:175], v[198:201], v[34:37]
	v_mfma_f32_16x16x32_bf16 v[34:37], v[186:189], v[202:205], v[34:37]
	v_mfma_f32_16x16x32_bf16 v[22:25], v[164:167], v[206:209], v[22:25]
	v_mfma_f32_16x16x32_bf16 v[22:25], v[168:171], v[210:213], v[22:25]
	v_mfma_f32_16x16x32_bf16 v[18:21], v[172:175], v[206:209], v[18:21]
	v_mfma_f32_16x16x32_bf16 v[18:21], v[186:189], v[210:213], v[18:21]
	v_mfma_f32_16x16x32_bf16 v[6:9], v[164:167], v[214:217], v[6:9]
	v_mfma_f32_16x16x32_bf16 v[6:9], v[168:171], v[218:221], v[6:9]
	v_mfma_f32_16x16x32_bf16 v[2:5], v[172:175], v[214:217], v[2:5]
	v_mfma_f32_16x16x32_bf16 v[2:5], v[186:189], v[218:221], v[2:5]
	s_barrier
	s_setprio 0
	s_add_i32 s47, s47, 2
	s_add_u32 s45, s45, 0x300000
	s_addc_u32 s46, s46, 0
	s_add_u32 s12, s12, 0x200000
	s_addc_u32 s13, s13, 0
	s_cmp_gt_u32 s47, 61
	s_cbranch_scc0 .LBB0_801
	s_and_b64 vcc, exec, s[8:9]
	s_cbranch_vccz .LBB0_804
	s_barrier

.LBB0_1217:
	ds_read_b128 v[146:149], v152
	ds_read_b128 v[156:159], v152 offset:1024
	ds_read_b128 v[160:163], v152 offset:2048
	ds_read_b128 v[164:167], v152 offset:3072
	ds_read_b128 v[168:171], v153
	ds_read_b128 v[172:175], v153 offset:1024
	ds_read_b128 v[176:179], v153 offset:2048
	ds_read_b128 v[180:183], v153 offset:3072
	s_add_u32 s22, s20, 0xfc000
	s_addc_u32 s23, s21, 0
	s_cmp_eq_u32 s43, 60
	s_cselect_b32 s26, s15, s22
	s_cselect_b32 s27, s5, s23
	s_cselect_b32 s24, s40, s41
	s_cselect_b32 s25, s13, s42
	s_add_u32 s22, s26, 0x100000
	s_addc_u32 s23, s27, 0
	s_add_i32 m0, s1, 0xc000
	ds_read_b128 v[184:187], v154
	ds_read_b128 v[188:191], v154 offset:1024
	ds_read_b128 v[192:195], v154 offset:2048
	ds_read_b128 v[196:199], v154 offset:3072
	ds_read_b128 v[206:209], v154 offset:4096
	ds_read_b128 v[212:215], v154 offset:5120
	ds_read_b128 v[220:223], v154 offset:6144
	ds_read_b128 v[224:227], v154 offset:7168
	global_load_lds_dwordx4 v138, s[20:21]
	s_add_i32 m0, s1, 0xe000
	s_nop 0
	global_load_lds_dwordx4 v140, s[20:21]
	s_waitcnt vmcnt(8)
	s_waitcnt lgkmcnt(0)
	s_setprio 1
	s_barrier
	v_mfma_f32_16x16x32_bf16 v[126:129], v[146:149], v[184:187], v[126:129]
	v_mfma_f32_16x16x32_bf16 v[126:129], v[156:159], v[188:191], v[126:129]
	v_mfma_f32_16x16x32_bf16 v[122:125], v[160:163], v[184:187], v[122:125]
	v_mfma_f32_16x16x32_bf16 v[122:125], v[164:167], v[188:191], v[122:125]
	v_mfma_f32_16x16x32_bf16 v[110:113], v[146:149], v[192:195], v[110:113]
	v_mfma_f32_16x16x32_bf16 v[110:113], v[156:159], v[196:199], v[110:113]
	v_mfma_f32_16x16x32_bf16 v[106:109], v[160:163], v[192:195], v[106:109]
	v_mfma_f32_16x16x32_bf16 v[106:109], v[164:167], v[196:199], v[106:109]
	v_mfma_f32_16x16x32_bf16 v[94:97], v[146:149], v[206:209], v[94:97]
	v_mfma_f32_16x16x32_bf16 v[94:97], v[156:159], v[212:215], v[94:97]
	v_mfma_f32_16x16x32_bf16 v[90:93], v[160:163], v[206:209], v[90:93]
	v_mfma_f32_16x16x32_bf16 v[90:93], v[164:167], v[212:215], v[90:93]
	v_mfma_f32_16x16x32_bf16 v[78:81], v[146:149], v[220:223], v[78:81]
	v_mfma_f32_16x16x32_bf16 v[78:81], v[156:159], v[224:227], v[78:81]
	v_mfma_f32_16x16x32_bf16 v[74:77], v[160:163], v[220:223], v[74:77]
	v_mfma_f32_16x16x32_bf16 v[74:77], v[164:167], v[224:227], v[74:77]
	s_setprio 0
	s_setprio 1
	v_mfma_f32_16x16x32_bf16 v[118:121], v[168:171], v[184:187], v[118:121]
	v_mfma_f32_16x16x32_bf16 v[118:121], v[172:175], v[188:191], v[118:121]
	v_mfma_f32_16x16x32_bf16 v[114:117], v[176:179], v[184:187], v[114:117]
	v_mfma_f32_16x16x32_bf16 v[114:117], v[180:183], v[188:191], v[114:117]
	v_mfma_f32_16x16x32_bf16 v[102:105], v[168:171], v[192:195], v[102:105]
	v_mfma_f32_16x16x32_bf16 v[102:105], v[172:175], v[196:199], v[102:105]
	v_mfma_f32_16x16x32_bf16 v[98:101], v[176:179], v[192:195], v[98:101]
	v_mfma_f32_16x16x32_bf16 v[98:101], v[180:183], v[196:199], v[98:101]
	v_mfma_f32_16x16x32_bf16 v[86:89], v[168:171], v[206:209], v[86:89]
	v_mfma_f32_16x16x32_bf16 v[86:89], v[172:175], v[212:215], v[86:89]
	v_mfma_f32_16x16x32_bf16 v[82:85], v[176:179], v[206:209], v[82:85]
	v_mfma_f32_16x16x32_bf16 v[82:85], v[180:183], v[212:215], v[82:85]
	v_mfma_f32_16x16x32_bf16 v[70:73], v[168:171], v[220:223], v[70:73]
	v_mfma_f32_16x16x32_bf16 v[70:73], v[172:175], v[224:227], v[70:73]
	v_mfma_f32_16x16x32_bf16 v[66:69], v[176:179], v[220:223], v[66:69]
	v_mfma_f32_16x16x32_bf16 v[66:69], v[180:183], v[224:227], v[66:69]
	s_barrier
	s_setprio 0
	s_add_i32 s44, s37, s0
	s_mov_b32 m0, s44
	ds_read_b128 v[184:187], v154 offset:16384
	ds_read_b128 v[188:191], v154 offset:17408
	ds_read_b128 v[192:195], v154 offset:18432
	ds_read_b128 v[196:199], v154 offset:19456
	ds_read_b128 v[206:209], v154 offset:20480
	ds_read_b128 v[212:215], v154 offset:21504
	ds_read_b128 v[220:223], v154 offset:22528
	ds_read_b128 v[224:227], v154 offset:23552
	global_load_lds_dwordx4 v132, s[24:25]
	s_add_i32 m0, s44, 0x2000
	s_add_u32 s44, s24, 0x4000
	s_addc_u32 s45, s25, 0
	s_add_i32 s46, s38, s0
	global_load_lds_dwordx4 v136, s[24:25]
	s_mov_b32 m0, s46
	s_nop 0
	global_load_lds_dwordx4 v132, s[44:45]
	s_add_i32 m0, s46, 0x2000
	s_nop 0
	global_load_lds_dwordx4 v136, s[44:45]
	s_mov_b32 m0, s1
	s_nop 0
	global_load_lds_dwordx4 v130, s[26:27]
	s_mov_b32 m0, s28
	s_nop 0
	global_load_lds_dwordx4 v134, s[26:27]
	s_waitcnt vmcnt(8)
	s_waitcnt lgkmcnt(0)
	s_setprio 1
	s_barrier
	v_mfma_f32_16x16x32_bf16 v[62:65], v[146:149], v[184:187], v[62:65]
	v_mfma_f32_16x16x32_bf16 v[62:65], v[156:159], v[188:191], v[62:65]
	v_mfma_f32_16x16x32_bf16 v[58:61], v[160:163], v[184:187], v[58:61]
	v_mfma_f32_16x16x32_bf16 v[58:61], v[164:167], v[188:191], v[58:61]
	v_mfma_f32_16x16x32_bf16 v[46:49], v[146:149], v[192:195], v[46:49]
	v_mfma_f32_16x16x32_bf16 v[46:49], v[156:159], v[196:199], v[46:49]
	v_mfma_f32_16x16x32_bf16 v[42:45], v[160:163], v[192:195], v[42:45]
	v_mfma_f32_16x16x32_bf16 v[42:45], v[164:167], v[196:199], v[42:45]
	v_mfma_f32_16x16x32_bf16 v[30:33], v[146:149], v[206:209], v[30:33]
	v_mfma_f32_16x16x32_bf16 v[30:33], v[156:159], v[212:215], v[30:33]
	v_mfma_f32_16x16x32_bf16 v[26:29], v[160:163], v[206:209], v[26:29]
	v_mfma_f32_16x16x32_bf16 v[26:29], v[164:167], v[212:215], v[26:29]
	v_mfma_f32_16x16x32_bf16 v[14:17], v[146:149], v[220:223], v[14:17]
	v_mfma_f32_16x16x32_bf16 v[14:17], v[156:159], v[224:227], v[14:17]
	v_mfma_f32_16x16x32_bf16 v[10:13], v[160:163], v[220:223], v[10:13]
	v_mfma_f32_16x16x32_bf16 v[10:13], v[164:167], v[224:227], v[10:13]
	s_setprio 0
	s_setprio 1
	v_mfma_f32_16x16x32_bf16 v[54:57], v[168:171], v[184:187], v[54:57]
	v_mfma_f32_16x16x32_bf16 v[54:57], v[172:175], v[188:191], v[54:57]
	v_mfma_f32_16x16x32_bf16 v[50:53], v[176:179], v[184:187], v[50:53]
	v_mfma_f32_16x16x32_bf16 v[50:53], v[180:183], v[188:191], v[50:53]
	v_mfma_f32_16x16x32_bf16 v[38:41], v[168:171], v[192:195], v[38:41]
	v_mfma_f32_16x16x32_bf16 v[38:41], v[172:175], v[196:199], v[38:41]
	v_mfma_f32_16x16x32_bf16 v[34:37], v[176:179], v[192:195], v[34:37]
	v_mfma_f32_16x16x32_bf16 v[34:37], v[180:183], v[196:199], v[34:37]
	v_mfma_f32_16x16x32_bf16 v[22:25], v[168:171], v[206:209], v[22:25]
	v_mfma_f32_16x16x32_bf16 v[22:25], v[172:175], v[212:215], v[22:25]
	v_mfma_f32_16x16x32_bf16 v[18:21], v[176:179], v[206:209], v[18:21]
	v_mfma_f32_16x16x32_bf16 v[18:21], v[180:183], v[212:215], v[18:21]
	v_mfma_f32_16x16x32_bf16 v[6:9], v[168:171], v[220:223], v[6:9]
	v_mfma_f32_16x16x32_bf16 v[6:9], v[172:175], v[224:227], v[6:9]
	v_mfma_f32_16x16x32_bf16 v[2:5], v[176:179], v[220:223], v[2:5]
	v_mfma_f32_16x16x32_bf16 v[2:5], v[180:183], v[224:227], v[2:5]
	s_barrier
	s_setprio 0
	s_add_i32 s44, 0, 0x18000
	v_add_u32_e32 v155, s44, v151
	s_add_i32 s45, 0, 0x1c000
	ds_read_b128 v[146:149], v155
	ds_read_b128 v[156:159], v155 offset:1024
	ds_read_b128 v[160:163], v155 offset:2048
	ds_read_b128 v[164:167], v155 offset:3072
	v_add_u32_e32 v155, s45, v151
	ds_read_b128 v[168:171], v155
	ds_read_b128 v[172:175], v155 offset:1024
	ds_read_b128 v[176:179], v155 offset:2048
	ds_read_b128 v[180:183], v155 offset:3072
	s_add_u32 s26, s26, 0x4000
	s_addc_u32 s27, s27, 0
	s_mov_b32 m0, s29
	ds_read_b128 v[184:187], v154 offset:32768
	ds_read_b128 v[188:191], v154 offset:33792
	ds_read_b128 v[192:195], v154 offset:34816
	ds_read_b128 v[196:199], v154 offset:35840
	ds_read_b128 v[206:209], v154 offset:36864
	ds_read_b128 v[212:215], v154 offset:37888
	ds_read_b128 v[220:223], v154 offset:38912
	ds_read_b128 v[224:227], v154 offset:39936
	global_load_lds_dwordx4 v130, s[26:27]
	s_mov_b32 m0, s30
	s_nop 0
	global_load_lds_dwordx4 v134, s[26:27]
	s_waitcnt vmcnt(8)
	s_waitcnt lgkmcnt(0)
	s_setprio 1
	s_barrier
	v_mfma_f32_16x16x32_bf16 v[126:129], v[146:149], v[184:187], v[126:129]
	v_mfma_f32_16x16x32_bf16 v[126:129], v[156:159], v[188:191], v[126:129]
	v_mfma_f32_16x16x32_bf16 v[122:125], v[160:163], v[184:187], v[122:125]
	v_mfma_f32_16x16x32_bf16 v[122:125], v[164:167], v[188:191], v[122:125]
	v_mfma_f32_16x16x32_bf16 v[110:113], v[146:149], v[192:195], v[110:113]
	v_mfma_f32_16x16x32_bf16 v[110:113], v[156:159], v[196:199], v[110:113]
	v_mfma_f32_16x16x32_bf16 v[106:109], v[160:163], v[192:195], v[106:109]
	v_mfma_f32_16x16x32_bf16 v[106:109], v[164:167], v[196:199], v[106:109]
	v_mfma_f32_16x16x32_bf16 v[94:97], v[146:149], v[206:209], v[94:97]
	v_mfma_f32_16x16x32_bf16 v[94:97], v[156:159], v[212:215], v[94:97]
	v_mfma_f32_16x16x32_bf16 v[90:93], v[160:163], v[206:209], v[90:93]
	v_mfma_f32_16x16x32_bf16 v[90:93], v[164:167], v[212:215], v[90:93]
	v_mfma_f32_16x16x32_bf16 v[78:81], v[146:149], v[220:223], v[78:81]
	v_mfma_f32_16x16x32_bf16 v[78:81], v[156:159], v[224:227], v[78:81]
	v_mfma_f32_16x16x32_bf16 v[74:77], v[160:163], v[220:223], v[74:77]
	v_mfma_f32_16x16x32_bf16 v[74:77], v[164:167], v[224:227], v[74:77]
	s_setprio 0
	s_setprio 1
	v_mfma_f32_16x16x32_bf16 v[118:121], v[168:171], v[184:187], v[118:121]
	v_mfma_f32_16x16x32_bf16 v[118:121], v[172:175], v[188:191], v[118:121]
	v_mfma_f32_16x16x32_bf16 v[114:117], v[176:179], v[184:187], v[114:117]
	v_mfma_f32_16x16x32_bf16 v[114:117], v[180:183], v[188:191], v[114:117]
	v_mfma_f32_16x16x32_bf16 v[102:105], v[168:171], v[192:195], v[102:105]
	v_mfma_f32_16x16x32_bf16 v[102:105], v[172:175], v[196:199], v[102:105]
	v_mfma_f32_16x16x32_bf16 v[98:101], v[176:179], v[192:195], v[98:101]
	v_mfma_f32_16x16x32_bf16 v[98:101], v[180:183], v[196:199], v[98:101]
	v_mfma_f32_16x16x32_bf16 v[86:89], v[168:171], v[206:209], v[86:89]
	v_mfma_f32_16x16x32_bf16 v[86:89], v[172:175], v[212:215], v[86:89]
	v_mfma_f32_16x16x32_bf16 v[82:85], v[176:179], v[206:209], v[82:85]
	v_mfma_f32_16x16x32_bf16 v[82:85], v[180:183], v[212:215], v[82:85]
	v_mfma_f32_16x16x32_bf16 v[70:73], v[168:171], v[220:223], v[70:73]
	v_mfma_f32_16x16x32_bf16 v[70:73], v[172:175], v[224:227], v[70:73]
	v_mfma_f32_16x16x32_bf16 v[66:69], v[176:179], v[220:223], v[66:69]
	v_mfma_f32_16x16x32_bf16 v[66:69], v[180:183], v[224:227], v[66:69]
	s_barrier
	s_setprio 0
	s_add_u32 s26, s24, 0x80000
	s_addc_u32 s27, s25, 0
	s_add_i32 s44, s44, s0
	s_mov_b32 m0, s44
	ds_read_b128 v[184:187], v154 offset:49152
	ds_read_b128 v[188:191], v154 offset:50176
	ds_read_b128 v[192:195], v154 offset:51200
	ds_read_b128 v[196:199], v154 offset:52224
	ds_read_b128 v[206:209], v154 offset:53248
	ds_read_b128 v[212:215], v154 offset:54272
	ds_read_b128 v[220:223], v154 offset:55296
	ds_read_b128 v[224:227], v154 offset:56320
	global_load_lds_dwordx4 v132, s[26:27]
	s_add_i32 m0, s44, 0x2000
	s_add_u32 s24, s24, 0x84000
	s_addc_u32 s25, s25, 0
	global_load_lds_dwordx4 v136, s[26:27]
	s_add_i32 s26, s45, s0
	s_mov_b32 m0, s26
	s_nop 0
	global_load_lds_dwordx4 v132, s[24:25]
	s_add_i32 m0, s26, 0x2000
	s_nop 0
	global_load_lds_dwordx4 v136, s[24:25]
	s_mov_b32 m0, s35
	s_nop 0
	global_load_lds_dwordx4 v130, s[22:23]
	s_mov_b32 m0, s36
	s_nop 0
	global_load_lds_dwordx4 v134, s[22:23]
	s_waitcnt vmcnt(8)
	s_waitcnt lgkmcnt(0)
	s_setprio 1
	s_barrier
	v_mfma_f32_16x16x32_bf16 v[62:65], v[146:149], v[184:187], v[62:65]
	v_mfma_f32_16x16x32_bf16 v[62:65], v[156:159], v[188:191], v[62:65]
	v_mfma_f32_16x16x32_bf16 v[58:61], v[160:163], v[184:187], v[58:61]
	v_mfma_f32_16x16x32_bf16 v[58:61], v[164:167], v[188:191], v[58:61]
	v_mfma_f32_16x16x32_bf16 v[46:49], v[146:149], v[192:195], v[46:49]
	v_mfma_f32_16x16x32_bf16 v[46:49], v[156:159], v[196:199], v[46:49]
	v_mfma_f32_16x16x32_bf16 v[42:45], v[160:163], v[192:195], v[42:45]
	v_mfma_f32_16x16x32_bf16 v[42:45], v[164:167], v[196:199], v[42:45]
	v_mfma_f32_16x16x32_bf16 v[30:33], v[146:149], v[206:209], v[30:33]
	v_mfma_f32_16x16x32_bf16 v[30:33], v[156:159], v[212:215], v[30:33]
	v_mfma_f32_16x16x32_bf16 v[26:29], v[160:163], v[206:209], v[26:29]
	v_mfma_f32_16x16x32_bf16 v[26:29], v[164:167], v[212:215], v[26:29]
	v_mfma_f32_16x16x32_bf16 v[14:17], v[146:149], v[220:223], v[14:17]
	v_mfma_f32_16x16x32_bf16 v[14:17], v[156:159], v[224:227], v[14:17]
	v_mfma_f32_16x16x32_bf16 v[10:13], v[160:163], v[220:223], v[10:13]
	v_mfma_f32_16x16x32_bf16 v[10:13], v[164:167], v[224:227], v[10:13]
	s_setprio 0
	s_setprio 1
	v_mfma_f32_16x16x32_bf16 v[54:57], v[168:171], v[184:187], v[54:57]
	v_mfma_f32_16x16x32_bf16 v[54:57], v[172:175], v[188:191], v[54:57]
	v_mfma_f32_16x16x32_bf16 v[50:53], v[176:179], v[184:187], v[50:53]
	v_mfma_f32_16x16x32_bf16 v[50:53], v[180:183], v[188:191], v[50:53]
	v_mfma_f32_16x16x32_bf16 v[38:41], v[168:171], v[192:195], v[38:41]
	v_mfma_f32_16x16x32_bf16 v[38:41], v[172:175], v[196:199], v[38:41]
	v_mfma_f32_16x16x32_bf16 v[34:37], v[176:179], v[192:195], v[34:37]
	v_mfma_f32_16x16x32_bf16 v[34:37], v[180:183], v[196:199], v[34:37]
	v_mfma_f32_16x16x32_bf16 v[22:25], v[168:171], v[206:209], v[22:25]
	v_mfma_f32_16x16x32_bf16 v[22:25], v[172:175], v[212:215], v[22:25]
	v_mfma_f32_16x16x32_bf16 v[18:21], v[176:179], v[206:209], v[18:21]
	v_mfma_f32_16x16x32_bf16 v[18:21], v[180:183], v[212:215], v[18:21]
	v_mfma_f32_16x16x32_bf16 v[6:9], v[168:171], v[220:223], v[6:9]
	v_mfma_f32_16x16x32_bf16 v[6:9], v[172:175], v[224:227], v[6:9]
	v_mfma_f32_16x16x32_bf16 v[2:5], v[176:179], v[220:223], v[2:5]
	v_mfma_f32_16x16x32_bf16 v[2:5], v[180:183], v[224:227], v[2:5]
	s_barrier
	s_setprio 0
	s_add_i32 s43, s43, 2
	s_add_u32 s41, s41, 0x100000
	s_addc_u32 s42, s42, 0
	s_add_u32 s20, s20, 0x200000
	s_addc_u32 s21, s21, 0
	s_cmp_gt_u32 s43, 61
	s_cbranch_scc0 .LBB0_1217
	s_and_b64 vcc, exec, s[8:9]
	s_cbranch_vccz .LBB0_1220
	s_barrier

.LBB0_1670:
	ds_read_b128 v[148:151], v143
	ds_read_b128 v[152:155], v143 offset:1024
	ds_read_b128 v[156:159], v143 offset:2048
	ds_read_b128 v[160:163], v143 offset:3072
	ds_read_b128 v[164:167], v144
	ds_read_b128 v[168:171], v144 offset:1024
	ds_read_b128 v[172:175], v144 offset:2048
	ds_read_b128 v[176:179], v144 offset:3072
	s_add_u32 s10, s6, 0x4000
	s_addc_u32 s11, s7, 0
	s_cmp_eq_u32 s28, 60
	s_cselect_b32 s18, s14, s10
	s_cselect_b32 s19, s15, s11
	s_cselect_b32 s16, s4, s26
	s_cselect_b32 s17, s5, s27
	s_add_u32 s10, s18, 0x8000
	s_addc_u32 s11, s19, 0
	s_mov_b32 m0, s29
	ds_read_b128 v[180:183], v145
	ds_read_b128 v[184:187], v145 offset:1024
	ds_read_b128 v[188:191], v145 offset:2048
	ds_read_b128 v[192:195], v145 offset:3072
	ds_read_b128 v[196:199], v145 offset:4096
	ds_read_b128 v[206:209], v145 offset:5120
	ds_read_b128 v[212:215], v145 offset:6144
	ds_read_b128 v[220:223], v145 offset:7168
	global_load_lds_dwordx4 v138, s[6:7]
	s_mov_b32 m0, s30
	s_nop 0
	global_load_lds_dwordx4 v140, s[6:7]
	s_waitcnt vmcnt(8)
	s_waitcnt lgkmcnt(0)
	s_setprio 1
	s_barrier
	v_mfma_f32_16x16x32_bf16 v[126:129], v[148:151], v[180:183], v[126:129]
	v_mfma_f32_16x16x32_bf16 v[126:129], v[152:155], v[184:187], v[126:129]
	v_mfma_f32_16x16x32_bf16 v[122:125], v[156:159], v[180:183], v[122:125]
	v_mfma_f32_16x16x32_bf16 v[122:125], v[160:163], v[184:187], v[122:125]
	v_mfma_f32_16x16x32_bf16 v[118:121], v[148:151], v[188:191], v[118:121]
	v_mfma_f32_16x16x32_bf16 v[118:121], v[152:155], v[192:195], v[118:121]
	v_mfma_f32_16x16x32_bf16 v[110:113], v[156:159], v[188:191], v[110:113]
	v_mfma_f32_16x16x32_bf16 v[110:113], v[160:163], v[192:195], v[110:113]
	v_mfma_f32_16x16x32_bf16 v[102:105], v[148:151], v[196:199], v[102:105]
	v_mfma_f32_16x16x32_bf16 v[102:105], v[152:155], v[206:209], v[102:105]
	v_mfma_f32_16x16x32_bf16 v[94:97], v[156:159], v[196:199], v[94:97]
	v_mfma_f32_16x16x32_bf16 v[94:97], v[160:163], v[206:209], v[94:97]
	v_mfma_f32_16x16x32_bf16 v[86:89], v[148:151], v[212:215], v[86:89]
	v_mfma_f32_16x16x32_bf16 v[86:89], v[152:155], v[220:223], v[86:89]
	v_mfma_f32_16x16x32_bf16 v[78:81], v[156:159], v[212:215], v[78:81]
	v_mfma_f32_16x16x32_bf16 v[78:81], v[160:163], v[220:223], v[78:81]
	s_setprio 0
	s_setprio 1
	v_mfma_f32_16x16x32_bf16 v[114:117], v[164:167], v[180:183], v[114:117]
	v_mfma_f32_16x16x32_bf16 v[114:117], v[168:171], v[184:187], v[114:117]
	v_mfma_f32_16x16x32_bf16 v[106:109], v[172:175], v[180:183], v[106:109]
	v_mfma_f32_16x16x32_bf16 v[106:109], v[176:179], v[184:187], v[106:109]
	v_mfma_f32_16x16x32_bf16 v[98:101], v[164:167], v[188:191], v[98:101]
	v_mfma_f32_16x16x32_bf16 v[98:101], v[168:171], v[192:195], v[98:101]
	v_mfma_f32_16x16x32_bf16 v[90:93], v[172:175], v[188:191], v[90:93]
	v_mfma_f32_16x16x32_bf16 v[90:93], v[176:179], v[192:195], v[90:93]
	v_mfma_f32_16x16x32_bf16 v[82:85], v[164:167], v[196:199], v[82:85]
	v_mfma_f32_16x16x32_bf16 v[82:85], v[168:171], v[206:209], v[82:85]
	v_mfma_f32_16x16x32_bf16 v[74:77], v[172:175], v[196:199], v[74:77]
	v_mfma_f32_16x16x32_bf16 v[74:77], v[176:179], v[206:209], v[74:77]
	v_mfma_f32_16x16x32_bf16 v[70:73], v[164:167], v[212:215], v[70:73]
	v_mfma_f32_16x16x32_bf16 v[70:73], v[168:171], v[220:223], v[70:73]
	v_mfma_f32_16x16x32_bf16 v[66:69], v[172:175], v[212:215], v[66:69]
	v_mfma_f32_16x16x32_bf16 v[66:69], v[176:179], v[220:223], v[66:69]
	s_barrier
	s_setprio 0
	s_mov_b32 m0, s31
	s_add_u32 s40, s16, 0x4000
	ds_read_b128 v[180:183], v145 offset:16384
	ds_read_b128 v[184:187], v145 offset:17408
	ds_read_b128 v[188:191], v145 offset:18432
	ds_read_b128 v[192:195], v145 offset:19456
	ds_read_b128 v[196:199], v145 offset:20480
	ds_read_b128 v[206:209], v145 offset:21504
	ds_read_b128 v[212:215], v145 offset:22528
	ds_read_b128 v[220:223], v145 offset:23552
	global_load_lds_dwordx4 v134, s[16:17]
	s_mov_b32 m0, s33
	s_addc_u32 s41, s17, 0
	global_load_lds_dwordx4 v130, s[16:17]
	s_mov_b32 m0, s34
	s_nop 0
	global_load_lds_dwordx4 v134, s[40:41]
	s_mov_b32 m0, s35
	s_nop 0
	global_load_lds_dwordx4 v130, s[40:41]
	s_mov_b32 m0, s1
	s_nop 0
	global_load_lds_dwordx4 v136, s[18:19]
	s_mov_b32 m0, s3
	s_nop 0
	global_load_lds_dwordx4 v132, s[18:19]
	s_waitcnt vmcnt(8)
	s_waitcnt lgkmcnt(0)
	s_setprio 1
	s_barrier
	v_mfma_f32_16x16x32_bf16 v[62:65], v[148:151], v[180:183], v[62:65]
	v_mfma_f32_16x16x32_bf16 v[62:65], v[152:155], v[184:187], v[62:65]
	v_mfma_f32_16x16x32_bf16 v[58:61], v[156:159], v[180:183], v[58:61]
	v_mfma_f32_16x16x32_bf16 v[58:61], v[160:163], v[184:187], v[58:61]
	v_mfma_f32_16x16x32_bf16 v[54:57], v[148:151], v[188:191], v[54:57]
	v_mfma_f32_16x16x32_bf16 v[54:57], v[152:155], v[192:195], v[54:57]
	v_mfma_f32_16x16x32_bf16 v[46:49], v[156:159], v[188:191], v[46:49]
	v_mfma_f32_16x16x32_bf16 v[46:49], v[160:163], v[192:195], v[46:49]
	v_mfma_f32_16x16x32_bf16 v[38:41], v[148:151], v[196:199], v[38:41]
	v_mfma_f32_16x16x32_bf16 v[38:41], v[152:155], v[206:209], v[38:41]
	v_mfma_f32_16x16x32_bf16 v[30:33], v[156:159], v[196:199], v[30:33]
	v_mfma_f32_16x16x32_bf16 v[30:33], v[160:163], v[206:209], v[30:33]
	v_mfma_f32_16x16x32_bf16 v[22:25], v[148:151], v[212:215], v[22:25]
	v_mfma_f32_16x16x32_bf16 v[22:25], v[152:155], v[220:223], v[22:25]
	v_mfma_f32_16x16x32_bf16 v[14:17], v[156:159], v[212:215], v[14:17]
	v_mfma_f32_16x16x32_bf16 v[14:17], v[160:163], v[220:223], v[14:17]
	s_setprio 0
	s_setprio 1
	v_mfma_f32_16x16x32_bf16 v[50:53], v[164:167], v[180:183], v[50:53]
	v_mfma_f32_16x16x32_bf16 v[50:53], v[168:171], v[184:187], v[50:53]
	v_mfma_f32_16x16x32_bf16 v[42:45], v[172:175], v[180:183], v[42:45]
	v_mfma_f32_16x16x32_bf16 v[42:45], v[176:179], v[184:187], v[42:45]
	v_mfma_f32_16x16x32_bf16 v[34:37], v[164:167], v[188:191], v[34:37]
	v_mfma_f32_16x16x32_bf16 v[34:37], v[168:171], v[192:195], v[34:37]
	v_mfma_f32_16x16x32_bf16 v[26:29], v[172:175], v[188:191], v[26:29]
	v_mfma_f32_16x16x32_bf16 v[26:29], v[176:179], v[192:195], v[26:29]
	v_mfma_f32_16x16x32_bf16 v[18:21], v[164:167], v[196:199], v[18:21]
	v_mfma_f32_16x16x32_bf16 v[18:21], v[168:171], v[206:209], v[18:21]
	v_mfma_f32_16x16x32_bf16 v[10:13], v[172:175], v[196:199], v[10:13]
	v_mfma_f32_16x16x32_bf16 v[10:13], v[176:179], v[206:209], v[10:13]
	v_mfma_f32_16x16x32_bf16 v[6:9], v[164:167], v[212:215], v[6:9]
	v_mfma_f32_16x16x32_bf16 v[6:9], v[168:171], v[220:223], v[6:9]
	v_mfma_f32_16x16x32_bf16 v[2:5], v[172:175], v[212:215], v[2:5]
	v_mfma_f32_16x16x32_bf16 v[2:5], v[176:179], v[220:223], v[2:5]
	s_barrier
	s_setprio 0
	ds_read_b128 v[148:151], v146
	ds_read_b128 v[152:155], v146 offset:1024
	ds_read_b128 v[156:159], v146 offset:2048
	ds_read_b128 v[160:163], v146 offset:3072
	ds_read_b128 v[164:167], v147
	ds_read_b128 v[168:171], v147 offset:1024
	ds_read_b128 v[172:175], v147 offset:2048
	ds_read_b128 v[176:179], v147 offset:3072
	s_add_u32 s18, s18, 0x4000
	s_addc_u32 s19, s19, 0
	s_mov_b32 m0, s20
	ds_read_b128 v[180:183], v145 offset:32768
	ds_read_b128 v[184:187], v145 offset:33792
	ds_read_b128 v[188:191], v145 offset:34816
	ds_read_b128 v[192:195], v145 offset:35840
	ds_read_b128 v[196:199], v145 offset:36864
	ds_read_b128 v[206:209], v145 offset:37888
	ds_read_b128 v[212:215], v145 offset:38912
	ds_read_b128 v[220:223], v145 offset:39936
	global_load_lds_dwordx4 v136, s[18:19]
	s_mov_b32 m0, s21
	s_nop 0
	global_load_lds_dwordx4 v132, s[18:19]
	s_waitcnt vmcnt(8)
	s_waitcnt lgkmcnt(0)
	s_setprio 1
	s_barrier
	v_mfma_f32_16x16x32_bf16 v[126:129], v[148:151], v[180:183], v[126:129]
	v_mfma_f32_16x16x32_bf16 v[126:129], v[152:155], v[184:187], v[126:129]
	v_mfma_f32_16x16x32_bf16 v[122:125], v[156:159], v[180:183], v[122:125]
	v_mfma_f32_16x16x32_bf16 v[122:125], v[160:163], v[184:187], v[122:125]
	v_mfma_f32_16x16x32_bf16 v[118:121], v[148:151], v[188:191], v[118:121]
	v_mfma_f32_16x16x32_bf16 v[118:121], v[152:155], v[192:195], v[118:121]
	v_mfma_f32_16x16x32_bf16 v[110:113], v[156:159], v[188:191], v[110:113]
	v_mfma_f32_16x16x32_bf16 v[110:113], v[160:163], v[192:195], v[110:113]
	v_mfma_f32_16x16x32_bf16 v[102:105], v[148:151], v[196:199], v[102:105]
	v_mfma_f32_16x16x32_bf16 v[102:105], v[152:155], v[206:209], v[102:105]
	v_mfma_f32_16x16x32_bf16 v[94:97], v[156:159], v[196:199], v[94:97]
	v_mfma_f32_16x16x32_bf16 v[94:97], v[160:163], v[206:209], v[94:97]
	v_mfma_f32_16x16x32_bf16 v[86:89], v[148:151], v[212:215], v[86:89]
	v_mfma_f32_16x16x32_bf16 v[86:89], v[152:155], v[220:223], v[86:89]
	v_mfma_f32_16x16x32_bf16 v[78:81], v[156:159], v[212:215], v[78:81]
	v_mfma_f32_16x16x32_bf16 v[78:81], v[160:163], v[220:223], v[78:81]
	s_setprio 0
	s_setprio 1
	v_mfma_f32_16x16x32_bf16 v[114:117], v[164:167], v[180:183], v[114:117]
	v_mfma_f32_16x16x32_bf16 v[114:117], v[168:171], v[184:187], v[114:117]
	v_mfma_f32_16x16x32_bf16 v[106:109], v[172:175], v[180:183], v[106:109]
	v_mfma_f32_16x16x32_bf16 v[106:109], v[176:179], v[184:187], v[106:109]
	v_mfma_f32_16x16x32_bf16 v[98:101], v[164:167], v[188:191], v[98:101]
	v_mfma_f32_16x16x32_bf16 v[98:101], v[168:171], v[192:195], v[98:101]
	v_mfma_f32_16x16x32_bf16 v[90:93], v[172:175], v[188:191], v[90:93]
	v_mfma_f32_16x16x32_bf16 v[90:93], v[176:179], v[192:195], v[90:93]
	v_mfma_f32_16x16x32_bf16 v[82:85], v[164:167], v[196:199], v[82:85]
	v_mfma_f32_16x16x32_bf16 v[82:85], v[168:171], v[206:209], v[82:85]
	v_mfma_f32_16x16x32_bf16 v[74:77], v[172:175], v[196:199], v[74:77]
	v_mfma_f32_16x16x32_bf16 v[74:77], v[176:179], v[206:209], v[74:77]
	v_mfma_f32_16x16x32_bf16 v[70:73], v[164:167], v[212:215], v[70:73]
	v_mfma_f32_16x16x32_bf16 v[70:73], v[168:171], v[220:223], v[70:73]
	v_mfma_f32_16x16x32_bf16 v[66:69], v[172:175], v[212:215], v[66:69]
	v_mfma_f32_16x16x32_bf16 v[66:69], v[176:179], v[220:223], v[66:69]
	s_barrier
	s_setprio 0
	s_add_u32 s18, s16, 0x20000
	s_addc_u32 s19, s17, 0
	s_mov_b32 m0, s36
	s_add_u32 s16, s16, 0x24000
	ds_read_b128 v[180:183], v145 offset:49152
	ds_read_b128 v[184:187], v145 offset:50176
	ds_read_b128 v[188:191], v145 offset:51200
	ds_read_b128 v[192:195], v145 offset:52224
	ds_read_b128 v[196:199], v145 offset:53248
	ds_read_b128 v[206:209], v145 offset:54272
	ds_read_b128 v[212:215], v145 offset:55296
	ds_read_b128 v[220:223], v145 offset:56320
	global_load_lds_dwordx4 v134, s[18:19]
	s_mov_b32 m0, s37
	s_addc_u32 s17, s17, 0
	global_load_lds_dwordx4 v130, s[18:19]
	s_mov_b32 m0, s38
	s_nop 0
	global_load_lds_dwordx4 v134, s[16:17]
	s_mov_b32 m0, s39
	s_nop 0
	global_load_lds_dwordx4 v130, s[16:17]
	s_mov_b32 m0, s24
	s_nop 0
	global_load_lds_dwordx4 v136, s[10:11]
	s_mov_b32 m0, s25
	s_nop 0
	global_load_lds_dwordx4 v132, s[10:11]
	s_waitcnt vmcnt(8)
	s_waitcnt lgkmcnt(0)
	s_setprio 1
	s_barrier
	v_mfma_f32_16x16x32_bf16 v[62:65], v[148:151], v[180:183], v[62:65]
	v_mfma_f32_16x16x32_bf16 v[62:65], v[152:155], v[184:187], v[62:65]
	v_mfma_f32_16x16x32_bf16 v[58:61], v[156:159], v[180:183], v[58:61]
	v_mfma_f32_16x16x32_bf16 v[58:61], v[160:163], v[184:187], v[58:61]
	v_mfma_f32_16x16x32_bf16 v[54:57], v[148:151], v[188:191], v[54:57]
	v_mfma_f32_16x16x32_bf16 v[54:57], v[152:155], v[192:195], v[54:57]
	v_mfma_f32_16x16x32_bf16 v[46:49], v[156:159], v[188:191], v[46:49]
	v_mfma_f32_16x16x32_bf16 v[46:49], v[160:163], v[192:195], v[46:49]
	v_mfma_f32_16x16x32_bf16 v[38:41], v[148:151], v[196:199], v[38:41]
	v_mfma_f32_16x16x32_bf16 v[38:41], v[152:155], v[206:209], v[38:41]
	v_mfma_f32_16x16x32_bf16 v[30:33], v[156:159], v[196:199], v[30:33]
	v_mfma_f32_16x16x32_bf16 v[30:33], v[160:163], v[206:209], v[30:33]
	v_mfma_f32_16x16x32_bf16 v[22:25], v[148:151], v[212:215], v[22:25]
	v_mfma_f32_16x16x32_bf16 v[22:25], v[152:155], v[220:223], v[22:25]
	v_mfma_f32_16x16x32_bf16 v[14:17], v[156:159], v[212:215], v[14:17]
	v_mfma_f32_16x16x32_bf16 v[14:17], v[160:163], v[220:223], v[14:17]
	s_setprio 0
	s_setprio 1
	v_mfma_f32_16x16x32_bf16 v[50:53], v[164:167], v[180:183], v[50:53]
	v_mfma_f32_16x16x32_bf16 v[50:53], v[168:171], v[184:187], v[50:53]
	v_mfma_f32_16x16x32_bf16 v[42:45], v[172:175], v[180:183], v[42:45]
	v_mfma_f32_16x16x32_bf16 v[42:45], v[176:179], v[184:187], v[42:45]
	v_mfma_f32_16x16x32_bf16 v[34:37], v[164:167], v[188:191], v[34:37]
	v_mfma_f32_16x16x32_bf16 v[34:37], v[168:171], v[192:195], v[34:37]
	v_mfma_f32_16x16x32_bf16 v[26:29], v[172:175], v[188:191], v[26:29]
	v_mfma_f32_16x16x32_bf16 v[26:29], v[176:179], v[192:195], v[26:29]
	v_mfma_f32_16x16x32_bf16 v[18:21], v[164:167], v[196:199], v[18:21]
	v_mfma_f32_16x16x32_bf16 v[18:21], v[168:171], v[206:209], v[18:21]
	v_mfma_f32_16x16x32_bf16 v[10:13], v[172:175], v[196:199], v[10:13]
	v_mfma_f32_16x16x32_bf16 v[10:13], v[176:179], v[206:209], v[10:13]
	v_mfma_f32_16x16x32_bf16 v[6:9], v[164:167], v[212:215], v[6:9]
	v_mfma_f32_16x16x32_bf16 v[6:9], v[168:171], v[220:223], v[6:9]
	v_mfma_f32_16x16x32_bf16 v[2:5], v[172:175], v[212:215], v[2:5]
	v_mfma_f32_16x16x32_bf16 v[2:5], v[176:179], v[220:223], v[2:5]
	s_barrier
	s_setprio 0
	s_add_i32 s28, s28, 2
	s_add_u32 s26, s26, 0x40000
	s_addc_u32 s27, s27, 0
	s_add_u32 s6, s6, 0x10000
	s_addc_u32 s7, s7, 0
	s_cmp_gt_u32 s28, 61
	s_cbranch_scc0 .LBB0_1670
	s_lshl_b32 s1, s2, 8
	v_and_or_b32 v132, v142, 15, s22
	v_lshrrev_b32_e32 v130, 1, v142
	v_and_or_b32 v130, v130, 24, s1
	v_ashrrev_i32_e32 v133, 31, v132
	v_or_b32_e32 v134, s23, v130
	v_lshlrev_b64 v[130:131], 11, v[132:133]
	v_lshl_add_u64 v[130:131], s[8:9], 0, v[130:131]
	v_lshlrev_b32_e32 v134, 1, v134
	v_mov_b32_e32 v135, 0
	v_lshl_add_u64 v[130:131], v[130:131], 0, v[134:135]
	v_cvt_pk_bf16_f32 v126, v126, v127
	v_cvt_pk_bf16_f32 v127, v128, v129
	v_cvt_pk_bf16_f32 v128, v122, v123
	v_cvt_pk_bf16_f32 v129, v124, v125
	global_store_dwordx4 v[130:131], v[126:129], off
	v_cvt_pk_bf16_f32 v114, v114, v115
	v_cvt_pk_bf16_f32 v115, v116, v117
	v_cvt_pk_bf16_f32 v116, v106, v107
	v_or_b32_e32 v106, 16, v132
	v_ashrrev_i32_e32 v107, 31, v106
	v_lshlrev_b64 v[106:107], 11, v[106:107]
	v_lshl_add_u64 v[106:107], s[8:9], 0, v[106:107]
	v_cvt_pk_bf16_f32 v117, v108, v109
	global_store_dwordx4 v[130:131], v[114:117], off offset:256
	s_mov_b32 s1, 0x40000
	s_mov_b64 s[2:3], 0x40000
	v_lshl_add_u64 v[114:115], v[106:107], 0, v[134:135]
	v_cvt_pk_bf16_f32 v106, v118, v119
	v_cvt_pk_bf16_f32 v107, v120, v121
	v_cvt_pk_bf16_f32 v108, v110, v111
	v_cvt_pk_bf16_f32 v109, v112, v113
	global_store_dwordx4 v[114:115], v[106:109], off
	v_cvt_pk_bf16_f32 v98, v98, v99
	v_cvt_pk_bf16_f32 v99, v100, v101
	v_cvt_pk_bf16_f32 v100, v90, v91
	v_or_b32_e32 v90, 32, v132
	v_ashrrev_i32_e32 v91, 31, v90
	v_lshlrev_b64 v[90:91], 11, v[90:91]
	v_lshl_add_u64 v[90:91], s[8:9], 0, v[90:91]
	v_cvt_pk_bf16_f32 v101, v92, v93
	global_store_dwordx4 v[114:115], v[98:101], off offset:256
	s_cmpk_lt_u32 s0, 0x100
	s_nop 0
	v_lshl_add_u64 v[98:99], v[90:91], 0, v[134:135]
	v_cvt_pk_bf16_f32 v90, v102, v103
	v_cvt_pk_bf16_f32 v91, v104, v105
	v_cvt_pk_bf16_f32 v92, v94, v95
	v_cvt_pk_bf16_f32 v93, v96, v97
	global_store_dwordx4 v[98:99], v[90:93], off
	v_cvt_pk_bf16_f32 v82, v82, v83
	v_cvt_pk_bf16_f32 v83, v84, v85
	v_cvt_pk_bf16_f32 v84, v74, v75
	v_or_b32_e32 v74, 48, v132
	v_ashrrev_i32_e32 v75, 31, v74
	v_lshlrev_b64 v[74:75], 11, v[74:75]
	v_lshl_add_u64 v[74:75], s[8:9], 0, v[74:75]
	v_cvt_pk_bf16_f32 v85, v76, v77
	global_store_dwordx4 v[98:99], v[82:85], off offset:256
	s_nop 1
	v_lshl_add_u64 v[82:83], v[74:75], 0, v[134:135]
	v_cvt_pk_bf16_f32 v74, v86, v87
	v_cvt_pk_bf16_f32 v75, v88, v89
	v_cvt_pk_bf16_f32 v76, v78, v79
	v_cvt_pk_bf16_f32 v77, v80, v81
	global_store_dwordx4 v[82:83], v[74:77], off
	v_cvt_pk_bf16_f32 v70, v70, v71
	v_cvt_pk_bf16_f32 v71, v72, v73
	v_cvt_pk_bf16_f32 v72, v66, v67
	v_cvt_pk_bf16_f32 v73, v68, v69
	global_store_dwordx4 v[82:83], v[70:73], off offset:256
	v_cvt_pk_bf16_f32 v62, v62, v63
	v_cvt_pk_bf16_f32 v63, v64, v65
	v_cvt_pk_bf16_f32 v64, v58, v59
	v_add_co_u32_e32 v58, vcc, s1, v130
	v_lshl_add_u64 v[66:67], v[130:131], 0, s[2:3]
	s_nop 0
	v_addc_co_u32_e32 v59, vcc, 0, v131, vcc
	s_mov_b32 s1, 0x48000
	v_cvt_pk_bf16_f32 v65, v60, v61
	global_store_dwordx4 v[58:59], v[62:65], off
	v_cvt_pk_bf16_f32 v50, v50, v51
	v_cvt_pk_bf16_f32 v51, v52, v53
	v_cvt_pk_bf16_f32 v52, v42, v43
	v_cvt_pk_bf16_f32 v53, v44, v45
	global_store_dwordx4 v[66:67], v[50:53], off offset:256
	s_mov_b64 s[2:3], 0x48000
	v_cvt_pk_bf16_f32 v42, v54, v55
	v_cvt_pk_bf16_f32 v43, v56, v57
	v_cvt_pk_bf16_f32 v44, v46, v47
	v_add_co_u32_e32 v46, vcc, s1, v130
	v_lshl_add_u64 v[50:51], v[130:131], 0, s[2:3]
	s_nop 0
	v_addc_co_u32_e32 v47, vcc, 0, v131, vcc
	s_mov_b32 s1, 0x50000
	v_cvt_pk_bf16_f32 v45, v48, v49
	global_store_dwordx4 v[46:47], v[42:45], off
	v_cvt_pk_bf16_f32 v34, v34, v35
	v_cvt_pk_bf16_f32 v35, v36, v37
	v_cvt_pk_bf16_f32 v36, v26, v27
	v_cvt_pk_bf16_f32 v37, v28, v29
	global_store_dwordx4 v[50:51], v[34:37], off offset:256
	s_mov_b64 s[2:3], 0x50000
	v_cvt_pk_bf16_f32 v26, v38, v39
	v_cvt_pk_bf16_f32 v27, v40, v41
	v_cvt_pk_bf16_f32 v28, v30, v31
	v_add_co_u32_e32 v30, vcc, s1, v130
	v_lshl_add_u64 v[34:35], v[130:131], 0, s[2:3]
	s_nop 0
	v_addc_co_u32_e32 v31, vcc, 0, v131, vcc
	s_mov_b32 s1, 0x58000
	v_cvt_pk_bf16_f32 v29, v32, v33
	global_store_dwordx4 v[30:31], v[26:29], off
	v_cvt_pk_bf16_f32 v18, v18, v19
	v_cvt_pk_bf16_f32 v19, v20, v21
	v_cvt_pk_bf16_f32 v20, v10, v11
	v_cvt_pk_bf16_f32 v21, v12, v13
	global_store_dwordx4 v[34:35], v[18:21], off offset:256
	s_mov_b64 s[2:3], 0x58000
	v_cvt_pk_bf16_f32 v10, v22, v23
	v_cvt_pk_bf16_f32 v11, v24, v25
	v_cvt_pk_bf16_f32 v12, v14, v15
	v_add_co_u32_e32 v14, vcc, s1, v130
	v_lshl_add_u64 v[18:19], v[130:131], 0, s[2:3]
	s_nop 0
	v_addc_co_u32_e32 v15, vcc, 0, v131, vcc
	v_cvt_pk_bf16_f32 v13, v16, v17
	global_store_dwordx4 v[14:15], v[10:13], off
	v_cvt_pk_bf16_f32 v6, v6, v7
	v_cvt_pk_bf16_f32 v7, v8, v9
	v_cvt_pk_bf16_f32 v8, v2, v3
	v_cvt_pk_bf16_f32 v9, v4, v5
	global_store_dwordx4 v[18:19], v[6:9], off offset:256
	s_waitcnt vmcnt(0)
	s_cbranch_scc0 .LBB0_1673
	s_barrier

.LBB0_1691:
	ds_read_b128 v[142:145], v150
	ds_read_b128 v[154:157], v150 offset:1024
	ds_read_b128 v[158:161], v150 offset:2048
	ds_read_b128 v[162:165], v150 offset:3072
	ds_read_b128 v[166:169], v151
	ds_read_b128 v[170:173], v151 offset:1024
	ds_read_b128 v[174:177], v151 offset:2048
	ds_read_b128 v[178:181], v151 offset:3072
	s_add_u32 s24, s22, 0xfc000
	s_addc_u32 s25, s23, 0
	s_cmp_eq_u32 s46, 60
	s_cselect_b32 s28, s17, s24
	s_cselect_b32 s29, s11, s25
	s_cselect_b32 s26, s43, s44
	s_cselect_b32 s27, s7, s45
	s_add_u32 s24, s28, 0x100000
	s_addc_u32 s25, s29, 0
	s_add_i32 m0, s30, 0xc000
	ds_read_b128 v[182:185], v152
	ds_read_b128 v[186:189], v152 offset:1024
	ds_read_b128 v[190:193], v152 offset:2048
	ds_read_b128 v[194:197], v152 offset:3072
	ds_read_b128 v[206:209], v152 offset:4096
	ds_read_b128 v[212:215], v152 offset:5120
	ds_read_b128 v[220:223], v152 offset:6144
	ds_read_b128 v[224:227], v152 offset:7168
	global_load_lds_dwordx4 v138, s[22:23]
	s_add_i32 m0, s30, 0xe000
	s_nop 0
	global_load_lds_dwordx4 v140, s[22:23]
	s_waitcnt vmcnt(8)
	s_waitcnt lgkmcnt(0)
	s_setprio 1
	s_barrier
	v_mfma_f32_16x16x32_bf16 v[126:129], v[142:145], v[182:185], v[126:129]
	v_mfma_f32_16x16x32_bf16 v[126:129], v[154:157], v[186:189], v[126:129]
	v_mfma_f32_16x16x32_bf16 v[122:125], v[158:161], v[182:185], v[122:125]
	v_mfma_f32_16x16x32_bf16 v[122:125], v[162:165], v[186:189], v[122:125]
	v_mfma_f32_16x16x32_bf16 v[110:113], v[142:145], v[190:193], v[110:113]
	v_mfma_f32_16x16x32_bf16 v[110:113], v[154:157], v[194:197], v[110:113]
	v_mfma_f32_16x16x32_bf16 v[106:109], v[158:161], v[190:193], v[106:109]
	v_mfma_f32_16x16x32_bf16 v[106:109], v[162:165], v[194:197], v[106:109]
	v_mfma_f32_16x16x32_bf16 v[94:97], v[142:145], v[206:209], v[94:97]
	v_mfma_f32_16x16x32_bf16 v[94:97], v[154:157], v[212:215], v[94:97]
	v_mfma_f32_16x16x32_bf16 v[90:93], v[158:161], v[206:209], v[90:93]
	v_mfma_f32_16x16x32_bf16 v[90:93], v[162:165], v[212:215], v[90:93]
	v_mfma_f32_16x16x32_bf16 v[78:81], v[142:145], v[220:223], v[78:81]
	v_mfma_f32_16x16x32_bf16 v[78:81], v[154:157], v[224:227], v[78:81]
	v_mfma_f32_16x16x32_bf16 v[74:77], v[158:161], v[220:223], v[74:77]
	v_mfma_f32_16x16x32_bf16 v[74:77], v[162:165], v[224:227], v[74:77]
	s_setprio 0
	s_setprio 1
	v_mfma_f32_16x16x32_bf16 v[118:121], v[166:169], v[182:185], v[118:121]
	v_mfma_f32_16x16x32_bf16 v[118:121], v[170:173], v[186:189], v[118:121]
	v_mfma_f32_16x16x32_bf16 v[114:117], v[174:177], v[182:185], v[114:117]
	v_mfma_f32_16x16x32_bf16 v[114:117], v[178:181], v[186:189], v[114:117]
	v_mfma_f32_16x16x32_bf16 v[102:105], v[166:169], v[190:193], v[102:105]
	v_mfma_f32_16x16x32_bf16 v[102:105], v[170:173], v[194:197], v[102:105]
	v_mfma_f32_16x16x32_bf16 v[98:101], v[174:177], v[190:193], v[98:101]
	v_mfma_f32_16x16x32_bf16 v[98:101], v[178:181], v[194:197], v[98:101]
	v_mfma_f32_16x16x32_bf16 v[86:89], v[166:169], v[206:209], v[86:89]
	v_mfma_f32_16x16x32_bf16 v[86:89], v[170:173], v[212:215], v[86:89]
	v_mfma_f32_16x16x32_bf16 v[82:85], v[174:177], v[206:209], v[82:85]
	v_mfma_f32_16x16x32_bf16 v[82:85], v[178:181], v[212:215], v[82:85]
	v_mfma_f32_16x16x32_bf16 v[70:73], v[166:169], v[220:223], v[70:73]
	v_mfma_f32_16x16x32_bf16 v[70:73], v[170:173], v[224:227], v[70:73]
	v_mfma_f32_16x16x32_bf16 v[66:69], v[174:177], v[220:223], v[66:69]
	v_mfma_f32_16x16x32_bf16 v[66:69], v[178:181], v[224:227], v[66:69]
	s_barrier
	s_setprio 0
	s_add_i32 s47, s40, s1
	s_mov_b32 m0, s47
	ds_read_b128 v[182:185], v152 offset:16384
	ds_read_b128 v[186:189], v152 offset:17408
	ds_read_b128 v[190:193], v152 offset:18432
	ds_read_b128 v[194:197], v152 offset:19456
	ds_read_b128 v[206:209], v152 offset:20480
	ds_read_b128 v[212:215], v152 offset:21504
	ds_read_b128 v[220:223], v152 offset:22528
	ds_read_b128 v[224:227], v152 offset:23552
	global_load_lds_dwordx4 v132, s[26:27]
	s_add_i32 m0, s47, 0x2000
	s_add_u32 s48, s26, 0x4000
	s_addc_u32 s49, s27, 0
	s_add_i32 s47, s41, s1
	global_load_lds_dwordx4 v136, s[26:27]
	s_mov_b32 m0, s47
	s_nop 0
	global_load_lds_dwordx4 v132, s[48:49]
	s_add_i32 m0, s47, 0x2000
	s_nop 0
	global_load_lds_dwordx4 v136, s[48:49]
	s_mov_b32 m0, s30
	s_nop 0
	global_load_lds_dwordx4 v130, s[28:29]
	s_mov_b32 m0, s31
	s_nop 0
	global_load_lds_dwordx4 v134, s[28:29]
	s_waitcnt vmcnt(8)
	s_waitcnt lgkmcnt(0)
	s_setprio 1
	s_barrier
	v_mfma_f32_16x16x32_bf16 v[62:65], v[142:145], v[182:185], v[62:65]
	v_mfma_f32_16x16x32_bf16 v[62:65], v[154:157], v[186:189], v[62:65]
	v_mfma_f32_16x16x32_bf16 v[58:61], v[158:161], v[182:185], v[58:61]
	v_mfma_f32_16x16x32_bf16 v[58:61], v[162:165], v[186:189], v[58:61]
	v_mfma_f32_16x16x32_bf16 v[46:49], v[142:145], v[190:193], v[46:49]
	v_mfma_f32_16x16x32_bf16 v[46:49], v[154:157], v[194:197], v[46:49]
	v_mfma_f32_16x16x32_bf16 v[42:45], v[158:161], v[190:193], v[42:45]
	v_mfma_f32_16x16x32_bf16 v[42:45], v[162:165], v[194:197], v[42:45]
	v_mfma_f32_16x16x32_bf16 v[30:33], v[142:145], v[206:209], v[30:33]
	v_mfma_f32_16x16x32_bf16 v[30:33], v[154:157], v[212:215], v[30:33]
	v_mfma_f32_16x16x32_bf16 v[26:29], v[158:161], v[206:209], v[26:29]
	v_mfma_f32_16x16x32_bf16 v[26:29], v[162:165], v[212:215], v[26:29]
	v_mfma_f32_16x16x32_bf16 v[14:17], v[142:145], v[220:223], v[14:17]
	v_mfma_f32_16x16x32_bf16 v[14:17], v[154:157], v[224:227], v[14:17]
	v_mfma_f32_16x16x32_bf16 v[10:13], v[158:161], v[220:223], v[10:13]
	v_mfma_f32_16x16x32_bf16 v[10:13], v[162:165], v[224:227], v[10:13]
	s_setprio 0
	s_setprio 1
	v_mfma_f32_16x16x32_bf16 v[54:57], v[166:169], v[182:185], v[54:57]
	v_mfma_f32_16x16x32_bf16 v[54:57], v[170:173], v[186:189], v[54:57]
	v_mfma_f32_16x16x32_bf16 v[50:53], v[174:177], v[182:185], v[50:53]
	v_mfma_f32_16x16x32_bf16 v[50:53], v[178:181], v[186:189], v[50:53]
	v_mfma_f32_16x16x32_bf16 v[38:41], v[166:169], v[190:193], v[38:41]
	v_mfma_f32_16x16x32_bf16 v[38:41], v[170:173], v[194:197], v[38:41]
	v_mfma_f32_16x16x32_bf16 v[34:37], v[174:177], v[190:193], v[34:37]
	v_mfma_f32_16x16x32_bf16 v[34:37], v[178:181], v[194:197], v[34:37]
	v_mfma_f32_16x16x32_bf16 v[22:25], v[166:169], v[206:209], v[22:25]
	v_mfma_f32_16x16x32_bf16 v[22:25], v[170:173], v[212:215], v[22:25]
	v_mfma_f32_16x16x32_bf16 v[18:21], v[174:177], v[206:209], v[18:21]
	v_mfma_f32_16x16x32_bf16 v[18:21], v[178:181], v[212:215], v[18:21]
	v_mfma_f32_16x16x32_bf16 v[6:9], v[166:169], v[220:223], v[6:9]
	v_mfma_f32_16x16x32_bf16 v[6:9], v[170:173], v[224:227], v[6:9]
	v_mfma_f32_16x16x32_bf16 v[2:5], v[174:177], v[220:223], v[2:5]
	v_mfma_f32_16x16x32_bf16 v[2:5], v[178:181], v[224:227], v[2:5]
	s_barrier
	s_setprio 0
	s_add_i32 s47, 0, 0x18000
	v_add_u32_e32 v146, s47, v149
	s_add_i32 s48, 0, 0x1c000
	ds_read_b128 v[142:145], v146
	ds_read_b128 v[154:157], v146 offset:1024
	ds_read_b128 v[158:161], v146 offset:2048
	ds_read_b128 v[162:165], v146 offset:3072
	v_add_u32_e32 v146, s48, v149
	ds_read_b128 v[166:169], v146
	ds_read_b128 v[170:173], v146 offset:1024
	ds_read_b128 v[174:177], v146 offset:2048
	ds_read_b128 v[178:181], v146 offset:3072
	s_add_u32 s28, s28, 0x4000
	s_addc_u32 s29, s29, 0
	s_mov_b32 m0, s33
	ds_read_b128 v[182:185], v152 offset:32768
	ds_read_b128 v[186:189], v152 offset:33792
	ds_read_b128 v[190:193], v152 offset:34816
	ds_read_b128 v[194:197], v152 offset:35840
	ds_read_b128 v[206:209], v152 offset:36864
	ds_read_b128 v[212:215], v152 offset:37888
	ds_read_b128 v[220:223], v152 offset:38912
	ds_read_b128 v[224:227], v152 offset:39936
	global_load_lds_dwordx4 v130, s[28:29]
	s_mov_b32 m0, s34
	s_nop 0
	global_load_lds_dwordx4 v134, s[28:29]
	s_waitcnt vmcnt(8)
	s_waitcnt lgkmcnt(0)
	s_setprio 1
	s_barrier
	v_mfma_f32_16x16x32_bf16 v[126:129], v[142:145], v[182:185], v[126:129]
	v_mfma_f32_16x16x32_bf16 v[126:129], v[154:157], v[186:189], v[126:129]
	v_mfma_f32_16x16x32_bf16 v[122:125], v[158:161], v[182:185], v[122:125]
	v_mfma_f32_16x16x32_bf16 v[122:125], v[162:165], v[186:189], v[122:125]
	v_mfma_f32_16x16x32_bf16 v[110:113], v[142:145], v[190:193], v[110:113]
	v_mfma_f32_16x16x32_bf16 v[110:113], v[154:157], v[194:197], v[110:113]
	v_mfma_f32_16x16x32_bf16 v[106:109], v[158:161], v[190:193], v[106:109]
	v_mfma_f32_16x16x32_bf16 v[106:109], v[162:165], v[194:197], v[106:109]
	v_mfma_f32_16x16x32_bf16 v[94:97], v[142:145], v[206:209], v[94:97]
	v_mfma_f32_16x16x32_bf16 v[94:97], v[154:157], v[212:215], v[94:97]
	v_mfma_f32_16x16x32_bf16 v[90:93], v[158:161], v[206:209], v[90:93]
	v_mfma_f32_16x16x32_bf16 v[90:93], v[162:165], v[212:215], v[90:93]
	v_mfma_f32_16x16x32_bf16 v[78:81], v[142:145], v[220:223], v[78:81]
	v_mfma_f32_16x16x32_bf16 v[78:81], v[154:157], v[224:227], v[78:81]
	v_mfma_f32_16x16x32_bf16 v[74:77], v[158:161], v[220:223], v[74:77]
	v_mfma_f32_16x16x32_bf16 v[74:77], v[162:165], v[224:227], v[74:77]
	s_setprio 0
	s_setprio 1
	v_mfma_f32_16x16x32_bf16 v[118:121], v[166:169], v[182:185], v[118:121]
	v_mfma_f32_16x16x32_bf16 v[118:121], v[170:173], v[186:189], v[118:121]
	v_mfma_f32_16x16x32_bf16 v[114:117], v[174:177], v[182:185], v[114:117]
	v_mfma_f32_16x16x32_bf16 v[114:117], v[178:181], v[186:189], v[114:117]
	v_mfma_f32_16x16x32_bf16 v[102:105], v[166:169], v[190:193], v[102:105]
	v_mfma_f32_16x16x32_bf16 v[102:105], v[170:173], v[194:197], v[102:105]
	v_mfma_f32_16x16x32_bf16 v[98:101], v[174:177], v[190:193], v[98:101]
	v_mfma_f32_16x16x32_bf16 v[98:101], v[178:181], v[194:197], v[98:101]
	v_mfma_f32_16x16x32_bf16 v[86:89], v[166:169], v[206:209], v[86:89]
	v_mfma_f32_16x16x32_bf16 v[86:89], v[170:173], v[212:215], v[86:89]
	v_mfma_f32_16x16x32_bf16 v[82:85], v[174:177], v[206:209], v[82:85]
	v_mfma_f32_16x16x32_bf16 v[82:85], v[178:181], v[212:215], v[82:85]
	v_mfma_f32_16x16x32_bf16 v[70:73], v[166:169], v[220:223], v[70:73]
	v_mfma_f32_16x16x32_bf16 v[70:73], v[170:173], v[224:227], v[70:73]
	v_mfma_f32_16x16x32_bf16 v[66:69], v[174:177], v[220:223], v[66:69]
	v_mfma_f32_16x16x32_bf16 v[66:69], v[178:181], v[224:227], v[66:69]
	s_barrier
	s_setprio 0
	s_add_u32 s28, s26, 0x10000
	s_addc_u32 s29, s27, 0
	s_add_i32 s47, s47, s1
	s_mov_b32 m0, s47
	ds_read_b128 v[182:185], v152 offset:49152
	ds_read_b128 v[186:189], v152 offset:50176
	ds_read_b128 v[190:193], v152 offset:51200
	ds_read_b128 v[194:197], v152 offset:52224
	ds_read_b128 v[206:209], v152 offset:53248
	ds_read_b128 v[212:215], v152 offset:54272
	ds_read_b128 v[220:223], v152 offset:55296
	ds_read_b128 v[224:227], v152 offset:56320
	global_load_lds_dwordx4 v132, s[28:29]
	s_add_i32 m0, s47, 0x2000
	s_add_u32 s26, s26, 0x14000
	s_addc_u32 s27, s27, 0
	global_load_lds_dwordx4 v136, s[28:29]
	s_add_i32 s28, s48, s1
	s_mov_b32 m0, s28
	s_nop 0
	global_load_lds_dwordx4 v132, s[26:27]
	s_add_i32 m0, s28, 0x2000
	s_nop 0
	global_load_lds_dwordx4 v136, s[26:27]
	s_mov_b32 m0, s38
	s_nop 0
	global_load_lds_dwordx4 v130, s[24:25]
	s_mov_b32 m0, s39
	s_nop 0
	global_load_lds_dwordx4 v134, s[24:25]
	s_waitcnt vmcnt(8)
	s_waitcnt lgkmcnt(0)
	s_setprio 1
	s_barrier
	v_mfma_f32_16x16x32_bf16 v[62:65], v[142:145], v[182:185], v[62:65]
	v_mfma_f32_16x16x32_bf16 v[62:65], v[154:157], v[186:189], v[62:65]
	v_mfma_f32_16x16x32_bf16 v[58:61], v[158:161], v[182:185], v[58:61]
	v_mfma_f32_16x16x32_bf16 v[58:61], v[162:165], v[186:189], v[58:61]
	v_mfma_f32_16x16x32_bf16 v[46:49], v[142:145], v[190:193], v[46:49]
	v_mfma_f32_16x16x32_bf16 v[46:49], v[154:157], v[194:197], v[46:49]
	v_mfma_f32_16x16x32_bf16 v[42:45], v[158:161], v[190:193], v[42:45]
	v_mfma_f32_16x16x32_bf16 v[42:45], v[162:165], v[194:197], v[42:45]
	v_mfma_f32_16x16x32_bf16 v[30:33], v[142:145], v[206:209], v[30:33]
	v_mfma_f32_16x16x32_bf16 v[30:33], v[154:157], v[212:215], v[30:33]
	v_mfma_f32_16x16x32_bf16 v[26:29], v[158:161], v[206:209], v[26:29]
	v_mfma_f32_16x16x32_bf16 v[26:29], v[162:165], v[212:215], v[26:29]
	v_mfma_f32_16x16x32_bf16 v[14:17], v[142:145], v[220:223], v[14:17]
	v_mfma_f32_16x16x32_bf16 v[14:17], v[154:157], v[224:227], v[14:17]
	v_mfma_f32_16x16x32_bf16 v[10:13], v[158:161], v[220:223], v[10:13]
	v_mfma_f32_16x16x32_bf16 v[10:13], v[162:165], v[224:227], v[10:13]
	s_setprio 0
	s_setprio 1
	v_mfma_f32_16x16x32_bf16 v[54:57], v[166:169], v[182:185], v[54:57]
	v_mfma_f32_16x16x32_bf16 v[54:57], v[170:173], v[186:189], v[54:57]
	v_mfma_f32_16x16x32_bf16 v[50:53], v[174:177], v[182:185], v[50:53]
	v_mfma_f32_16x16x32_bf16 v[50:53], v[178:181], v[186:189], v[50:53]
	v_mfma_f32_16x16x32_bf16 v[38:41], v[166:169], v[190:193], v[38:41]
	v_mfma_f32_16x16x32_bf16 v[38:41], v[170:173], v[194:197], v[38:41]
	v_mfma_f32_16x16x32_bf16 v[34:37], v[174:177], v[190:193], v[34:37]
	v_mfma_f32_16x16x32_bf16 v[34:37], v[178:181], v[194:197], v[34:37]
	v_mfma_f32_16x16x32_bf16 v[22:25], v[166:169], v[206:209], v[22:25]
	v_mfma_f32_16x16x32_bf16 v[22:25], v[170:173], v[212:215], v[22:25]
	v_mfma_f32_16x16x32_bf16 v[18:21], v[174:177], v[206:209], v[18:21]
	v_mfma_f32_16x16x32_bf16 v[18:21], v[178:181], v[212:215], v[18:21]
	v_mfma_f32_16x16x32_bf16 v[6:9], v[166:169], v[220:223], v[6:9]
	v_mfma_f32_16x16x32_bf16 v[6:9], v[170:173], v[224:227], v[6:9]
	v_mfma_f32_16x16x32_bf16 v[2:5], v[174:177], v[220:223], v[2:5]
	v_mfma_f32_16x16x32_bf16 v[2:5], v[178:181], v[224:227], v[2:5]
	s_barrier
	s_setprio 0
	s_add_i32 s46, s46, 2
	s_add_u32 s44, s44, 0x20000
	s_addc_u32 s45, s45, 0
	s_add_u32 s22, s22, 0x200000
	s_addc_u32 s23, s23, 0
	s_cmp_gt_u32 s46, 61
	s_cbranch_scc0 .LBB0_1691
	s_lshl_b32 s7, s10, 8
	v_mov_b32_e32 v144, v147
	s_add_i32 s7, s7, s36
	v_cndmask_b32_e64 v145, 0, 1, s[2:3]
	v_and_or_b32 v142, v144, 15, s7
	v_ashrrev_i32_e32 v143, 31, v142
	v_mov_b32_e32 v146, 0x3e0293ee
	v_cmp_ne_u32_e64 s[10:11], 1, v145
	s_andn2_b64 vcc, exec, s[2:3]
	v_mov_b32_e32 v148, 0x3e0293ee
	s_cbranch_vccnz .LBB0_1694
	v_readlane_b32 s22, v245, 16
	v_readlane_b32 s23, v245, 17
	s_nop 1
	v_lshl_add_u64 v[154:155], v[142:143], 2, s[22:23]
	global_load_dword v145, v[154:155], off
	s_waitcnt vmcnt(0)
	v_mul_f32_e32 v148, 0x3e0293ee, v145

.LBB0_1718:
	ds_read_b128 v[152:155], v147
	ds_read_b128 v[156:159], v147 offset:1024
	ds_read_b128 v[160:163], v147 offset:2048
	ds_read_b128 v[164:167], v147 offset:3072
	ds_read_b128 v[168:171], v148
	ds_read_b128 v[172:175], v148 offset:1024
	ds_read_b128 v[176:179], v148 offset:2048
	ds_read_b128 v[180:183], v148 offset:3072
	s_add_u32 s18, s16, 0x4000
	s_addc_u32 s19, s17, 0
	s_cmp_eq_u32 s50, 60
	s_cselect_b32 s22, s14, s18
	s_cselect_b32 s23, s15, s19
	s_cselect_b32 s20, s47, s48
	s_cselect_b32 s21, s46, s49
	s_add_u32 s18, s22, 0x8000
	s_addc_u32 s19, s23, 0
	s_mov_b32 m0, s31
	ds_read_b128 v[184:187], v149
	ds_read_b128 v[188:191], v149 offset:1024
	ds_read_b128 v[192:195], v149 offset:2048
	ds_read_b128 v[196:199], v149 offset:3072
	ds_read_b128 v[206:209], v149 offset:4096
	ds_read_b128 v[212:215], v149 offset:5120
	ds_read_b128 v[220:223], v149 offset:6144
	ds_read_b128 v[224:227], v149 offset:7168
	global_load_lds_dwordx4 v140, s[16:17]
	s_mov_b32 m0, s33
	s_nop 0
	global_load_lds_dwordx4 v142, s[16:17]
	s_waitcnt vmcnt(8)
	s_waitcnt lgkmcnt(0)
	s_setprio 1
	s_barrier
	v_mfma_f32_16x16x32_bf16 v[126:129], v[152:155], v[184:187], v[126:129]
	v_mfma_f32_16x16x32_bf16 v[126:129], v[156:159], v[188:191], v[126:129]
	v_mfma_f32_16x16x32_bf16 v[122:125], v[160:163], v[184:187], v[122:125]
	v_mfma_f32_16x16x32_bf16 v[122:125], v[164:167], v[188:191], v[122:125]
	v_mfma_f32_16x16x32_bf16 v[118:121], v[152:155], v[192:195], v[118:121]
	v_mfma_f32_16x16x32_bf16 v[118:121], v[156:159], v[196:199], v[118:121]
	v_mfma_f32_16x16x32_bf16 v[110:113], v[160:163], v[192:195], v[110:113]
	v_mfma_f32_16x16x32_bf16 v[110:113], v[164:167], v[196:199], v[110:113]
	v_mfma_f32_16x16x32_bf16 v[102:105], v[152:155], v[206:209], v[102:105]
	v_mfma_f32_16x16x32_bf16 v[102:105], v[156:159], v[212:215], v[102:105]
	v_mfma_f32_16x16x32_bf16 v[94:97], v[160:163], v[206:209], v[94:97]
	v_mfma_f32_16x16x32_bf16 v[94:97], v[164:167], v[212:215], v[94:97]
	v_mfma_f32_16x16x32_bf16 v[86:89], v[152:155], v[220:223], v[86:89]
	v_mfma_f32_16x16x32_bf16 v[86:89], v[156:159], v[224:227], v[86:89]
	v_mfma_f32_16x16x32_bf16 v[78:81], v[160:163], v[220:223], v[78:81]
	v_mfma_f32_16x16x32_bf16 v[78:81], v[164:167], v[224:227], v[78:81]
	s_setprio 0
	s_setprio 1
	v_mfma_f32_16x16x32_bf16 v[114:117], v[168:171], v[184:187], v[114:117]
	v_mfma_f32_16x16x32_bf16 v[114:117], v[172:175], v[188:191], v[114:117]
	v_mfma_f32_16x16x32_bf16 v[106:109], v[176:179], v[184:187], v[106:109]
	v_mfma_f32_16x16x32_bf16 v[106:109], v[180:183], v[188:191], v[106:109]
	v_mfma_f32_16x16x32_bf16 v[98:101], v[168:171], v[192:195], v[98:101]
	v_mfma_f32_16x16x32_bf16 v[98:101], v[172:175], v[196:199], v[98:101]
	v_mfma_f32_16x16x32_bf16 v[90:93], v[176:179], v[192:195], v[90:93]
	v_mfma_f32_16x16x32_bf16 v[90:93], v[180:183], v[196:199], v[90:93]
	v_mfma_f32_16x16x32_bf16 v[82:85], v[168:171], v[206:209], v[82:85]
	v_mfma_f32_16x16x32_bf16 v[82:85], v[172:175], v[212:215], v[82:85]
	v_mfma_f32_16x16x32_bf16 v[74:77], v[176:179], v[206:209], v[74:77]
	v_mfma_f32_16x16x32_bf16 v[74:77], v[180:183], v[212:215], v[74:77]
	v_mfma_f32_16x16x32_bf16 v[70:73], v[168:171], v[220:223], v[70:73]
	v_mfma_f32_16x16x32_bf16 v[70:73], v[172:175], v[224:227], v[70:73]
	v_mfma_f32_16x16x32_bf16 v[66:69], v[176:179], v[220:223], v[66:69]
	v_mfma_f32_16x16x32_bf16 v[66:69], v[180:183], v[224:227], v[66:69]
	s_barrier
	s_setprio 0
	s_mov_b32 m0, s36
	s_add_u32 s52, s20, 0x4000
	ds_read_b128 v[184:187], v149 offset:16384
	ds_read_b128 v[188:191], v149 offset:17408
	ds_read_b128 v[192:195], v149 offset:18432
	ds_read_b128 v[196:199], v149 offset:19456
	ds_read_b128 v[206:209], v149 offset:20480
	ds_read_b128 v[212:215], v149 offset:21504
	ds_read_b128 v[220:223], v149 offset:22528
	ds_read_b128 v[224:227], v149 offset:23552
	global_load_lds_dwordx4 v134, s[20:21]
	s_mov_b32 m0, s37
	s_addc_u32 s53, s21, 0
	global_load_lds_dwordx4 v130, s[20:21]
	s_mov_b32 m0, s38
	s_nop 0
	global_load_lds_dwordx4 v134, s[52:53]
	s_mov_b32 m0, s39
	s_nop 0
	global_load_lds_dwordx4 v130, s[52:53]
	s_mov_b32 m0, s1
	s_nop 0
	global_load_lds_dwordx4 v136, s[22:23]
	s_mov_b32 m0, s24
	s_nop 0
	global_load_lds_dwordx4 v132, s[22:23]
	s_waitcnt vmcnt(8)
	s_waitcnt lgkmcnt(0)
	s_setprio 1
	s_barrier
	v_mfma_f32_16x16x32_bf16 v[62:65], v[152:155], v[184:187], v[62:65]
	v_mfma_f32_16x16x32_bf16 v[62:65], v[156:159], v[188:191], v[62:65]
	v_mfma_f32_16x16x32_bf16 v[58:61], v[160:163], v[184:187], v[58:61]
	v_mfma_f32_16x16x32_bf16 v[58:61], v[164:167], v[188:191], v[58:61]
	v_mfma_f32_16x16x32_bf16 v[54:57], v[152:155], v[192:195], v[54:57]
	v_mfma_f32_16x16x32_bf16 v[54:57], v[156:159], v[196:199], v[54:57]
	v_mfma_f32_16x16x32_bf16 v[46:49], v[160:163], v[192:195], v[46:49]
	v_mfma_f32_16x16x32_bf16 v[46:49], v[164:167], v[196:199], v[46:49]
	v_mfma_f32_16x16x32_bf16 v[38:41], v[152:155], v[206:209], v[38:41]
	v_mfma_f32_16x16x32_bf16 v[38:41], v[156:159], v[212:215], v[38:41]
	v_mfma_f32_16x16x32_bf16 v[30:33], v[160:163], v[206:209], v[30:33]
	v_mfma_f32_16x16x32_bf16 v[30:33], v[164:167], v[212:215], v[30:33]
	v_mfma_f32_16x16x32_bf16 v[22:25], v[152:155], v[220:223], v[22:25]
	v_mfma_f32_16x16x32_bf16 v[22:25], v[156:159], v[224:227], v[22:25]
	v_mfma_f32_16x16x32_bf16 v[14:17], v[160:163], v[220:223], v[14:17]
	v_mfma_f32_16x16x32_bf16 v[14:17], v[164:167], v[224:227], v[14:17]
	s_setprio 0
	s_setprio 1
	v_mfma_f32_16x16x32_bf16 v[50:53], v[168:171], v[184:187], v[50:53]
	v_mfma_f32_16x16x32_bf16 v[50:53], v[172:175], v[188:191], v[50:53]
	v_mfma_f32_16x16x32_bf16 v[42:45], v[176:179], v[184:187], v[42:45]
	v_mfma_f32_16x16x32_bf16 v[42:45], v[180:183], v[188:191], v[42:45]
	v_mfma_f32_16x16x32_bf16 v[34:37], v[168:171], v[192:195], v[34:37]
	v_mfma_f32_16x16x32_bf16 v[34:37], v[172:175], v[196:199], v[34:37]
	v_mfma_f32_16x16x32_bf16 v[26:29], v[176:179], v[192:195], v[26:29]
	v_mfma_f32_16x16x32_bf16 v[26:29], v[180:183], v[196:199], v[26:29]
	v_mfma_f32_16x16x32_bf16 v[18:21], v[168:171], v[206:209], v[18:21]
	v_mfma_f32_16x16x32_bf16 v[18:21], v[172:175], v[212:215], v[18:21]
	v_mfma_f32_16x16x32_bf16 v[10:13], v[176:179], v[206:209], v[10:13]
	v_mfma_f32_16x16x32_bf16 v[10:13], v[180:183], v[212:215], v[10:13]
	v_mfma_f32_16x16x32_bf16 v[6:9], v[168:171], v[220:223], v[6:9]
	v_mfma_f32_16x16x32_bf16 v[6:9], v[172:175], v[224:227], v[6:9]
	v_mfma_f32_16x16x32_bf16 v[2:5], v[176:179], v[220:223], v[2:5]
	v_mfma_f32_16x16x32_bf16 v[2:5], v[180:183], v[224:227], v[2:5]
	s_barrier
	s_setprio 0
	ds_read_b128 v[152:155], v150
	ds_read_b128 v[156:159], v150 offset:1024
	ds_read_b128 v[160:163], v150 offset:2048
	ds_read_b128 v[164:167], v150 offset:3072
	ds_read_b128 v[168:171], v151
	ds_read_b128 v[172:175], v151 offset:1024
	ds_read_b128 v[176:179], v151 offset:2048
	ds_read_b128 v[180:183], v151 offset:3072
	s_add_u32 s22, s22, 0x4000
	s_addc_u32 s23, s23, 0
	s_mov_b32 m0, s25
	ds_read_b128 v[184:187], v149 offset:32768
	ds_read_b128 v[188:191], v149 offset:33792
	ds_read_b128 v[192:195], v149 offset:34816
	ds_read_b128 v[196:199], v149 offset:35840
	ds_read_b128 v[206:209], v149 offset:36864
	ds_read_b128 v[212:215], v149 offset:37888
	ds_read_b128 v[220:223], v149 offset:38912
	ds_read_b128 v[224:227], v149 offset:39936
	global_load_lds_dwordx4 v136, s[22:23]
	s_mov_b32 m0, s26
	s_nop 0
	global_load_lds_dwordx4 v132, s[22:23]
	s_waitcnt vmcnt(8)
	s_waitcnt lgkmcnt(0)
	s_setprio 1
	s_barrier
	v_mfma_f32_16x16x32_bf16 v[126:129], v[152:155], v[184:187], v[126:129]
	v_mfma_f32_16x16x32_bf16 v[126:129], v[156:159], v[188:191], v[126:129]
	v_mfma_f32_16x16x32_bf16 v[122:125], v[160:163], v[184:187], v[122:125]
	v_mfma_f32_16x16x32_bf16 v[122:125], v[164:167], v[188:191], v[122:125]
	v_mfma_f32_16x16x32_bf16 v[118:121], v[152:155], v[192:195], v[118:121]
	v_mfma_f32_16x16x32_bf16 v[118:121], v[156:159], v[196:199], v[118:121]
	v_mfma_f32_16x16x32_bf16 v[110:113], v[160:163], v[192:195], v[110:113]
	v_mfma_f32_16x16x32_bf16 v[110:113], v[164:167], v[196:199], v[110:113]
	v_mfma_f32_16x16x32_bf16 v[102:105], v[152:155], v[206:209], v[102:105]
	v_mfma_f32_16x16x32_bf16 v[102:105], v[156:159], v[212:215], v[102:105]
	v_mfma_f32_16x16x32_bf16 v[94:97], v[160:163], v[206:209], v[94:97]
	v_mfma_f32_16x16x32_bf16 v[94:97], v[164:167], v[212:215], v[94:97]
	v_mfma_f32_16x16x32_bf16 v[86:89], v[152:155], v[220:223], v[86:89]
	v_mfma_f32_16x16x32_bf16 v[86:89], v[156:159], v[224:227], v[86:89]
	v_mfma_f32_16x16x32_bf16 v[78:81], v[160:163], v[220:223], v[78:81]
	v_mfma_f32_16x16x32_bf16 v[78:81], v[164:167], v[224:227], v[78:81]
	s_setprio 0
	s_setprio 1
	v_mfma_f32_16x16x32_bf16 v[114:117], v[168:171], v[184:187], v[114:117]
	v_mfma_f32_16x16x32_bf16 v[114:117], v[172:175], v[188:191], v[114:117]
	v_mfma_f32_16x16x32_bf16 v[106:109], v[176:179], v[184:187], v[106:109]
	v_mfma_f32_16x16x32_bf16 v[106:109], v[180:183], v[188:191], v[106:109]
	v_mfma_f32_16x16x32_bf16 v[98:101], v[168:171], v[192:195], v[98:101]
	v_mfma_f32_16x16x32_bf16 v[98:101], v[172:175], v[196:199], v[98:101]
	v_mfma_f32_16x16x32_bf16 v[90:93], v[176:179], v[192:195], v[90:93]
	v_mfma_f32_16x16x32_bf16 v[90:93], v[180:183], v[196:199], v[90:93]
	v_mfma_f32_16x16x32_bf16 v[82:85], v[168:171], v[206:209], v[82:85]
	v_mfma_f32_16x16x32_bf16 v[82:85], v[172:175], v[212:215], v[82:85]
	v_mfma_f32_16x16x32_bf16 v[74:77], v[176:179], v[206:209], v[74:77]
	v_mfma_f32_16x16x32_bf16 v[74:77], v[180:183], v[212:215], v[74:77]
	v_mfma_f32_16x16x32_bf16 v[70:73], v[168:171], v[220:223], v[70:73]
	v_mfma_f32_16x16x32_bf16 v[70:73], v[172:175], v[224:227], v[70:73]
	v_mfma_f32_16x16x32_bf16 v[66:69], v[176:179], v[220:223], v[66:69]
	v_mfma_f32_16x16x32_bf16 v[66:69], v[180:183], v[224:227], v[66:69]
	s_barrier
	s_setprio 0
	s_add_u32 s22, s20, 0x20000
	s_addc_u32 s23, s21, 0
	s_mov_b32 m0, s40
	s_add_u32 s20, s20, 0x24000
	ds_read_b128 v[184:187], v149 offset:49152
	ds_read_b128 v[188:191], v149 offset:50176
	ds_read_b128 v[192:195], v149 offset:51200
	ds_read_b128 v[196:199], v149 offset:52224
	ds_read_b128 v[206:209], v149 offset:53248
	ds_read_b128 v[212:215], v149 offset:54272
	ds_read_b128 v[220:223], v149 offset:55296
	ds_read_b128 v[224:227], v149 offset:56320
	global_load_lds_dwordx4 v134, s[22:23]
	s_mov_b32 m0, s41
	s_addc_u32 s21, s21, 0
	global_load_lds_dwordx4 v130, s[22:23]
	s_mov_b32 m0, s42
	s_nop 0
	global_load_lds_dwordx4 v134, s[20:21]
	s_mov_b32 m0, s43
	s_nop 0
	global_load_lds_dwordx4 v130, s[20:21]
	s_mov_b32 m0, s29
	s_nop 0
	global_load_lds_dwordx4 v136, s[18:19]
	s_mov_b32 m0, s30
	s_nop 0
	global_load_lds_dwordx4 v132, s[18:19]
	s_waitcnt vmcnt(8)
	s_waitcnt lgkmcnt(0)
	s_setprio 1
	s_barrier
	v_mfma_f32_16x16x32_bf16 v[62:65], v[152:155], v[184:187], v[62:65]
	v_mfma_f32_16x16x32_bf16 v[62:65], v[156:159], v[188:191], v[62:65]
	v_mfma_f32_16x16x32_bf16 v[58:61], v[160:163], v[184:187], v[58:61]
	v_mfma_f32_16x16x32_bf16 v[58:61], v[164:167], v[188:191], v[58:61]
	v_mfma_f32_16x16x32_bf16 v[54:57], v[152:155], v[192:195], v[54:57]
	v_mfma_f32_16x16x32_bf16 v[54:57], v[156:159], v[196:199], v[54:57]
	v_mfma_f32_16x16x32_bf16 v[46:49], v[160:163], v[192:195], v[46:49]
	v_mfma_f32_16x16x32_bf16 v[46:49], v[164:167], v[196:199], v[46:49]
	v_mfma_f32_16x16x32_bf16 v[38:41], v[152:155], v[206:209], v[38:41]
	v_mfma_f32_16x16x32_bf16 v[38:41], v[156:159], v[212:215], v[38:41]
	v_mfma_f32_16x16x32_bf16 v[30:33], v[160:163], v[206:209], v[30:33]
	v_mfma_f32_16x16x32_bf16 v[30:33], v[164:167], v[212:215], v[30:33]
	v_mfma_f32_16x16x32_bf16 v[22:25], v[152:155], v[220:223], v[22:25]
	v_mfma_f32_16x16x32_bf16 v[22:25], v[156:159], v[224:227], v[22:25]
	v_mfma_f32_16x16x32_bf16 v[14:17], v[160:163], v[220:223], v[14:17]
	v_mfma_f32_16x16x32_bf16 v[14:17], v[164:167], v[224:227], v[14:17]
	s_setprio 0
	s_setprio 1
	v_mfma_f32_16x16x32_bf16 v[50:53], v[168:171], v[184:187], v[50:53]
	v_mfma_f32_16x16x32_bf16 v[50:53], v[172:175], v[188:191], v[50:53]
	v_mfma_f32_16x16x32_bf16 v[42:45], v[176:179], v[184:187], v[42:45]
	v_mfma_f32_16x16x32_bf16 v[42:45], v[180:183], v[188:191], v[42:45]
	v_mfma_f32_16x16x32_bf16 v[34:37], v[168:171], v[192:195], v[34:37]
	v_mfma_f32_16x16x32_bf16 v[34:37], v[172:175], v[196:199], v[34:37]
	v_mfma_f32_16x16x32_bf16 v[26:29], v[176:179], v[192:195], v[26:29]
	v_mfma_f32_16x16x32_bf16 v[26:29], v[180:183], v[196:199], v[26:29]
	v_mfma_f32_16x16x32_bf16 v[18:21], v[168:171], v[206:209], v[18:21]
	v_mfma_f32_16x16x32_bf16 v[18:21], v[172:175], v[212:215], v[18:21]
	v_mfma_f32_16x16x32_bf16 v[10:13], v[176:179], v[206:209], v[10:13]
	v_mfma_f32_16x16x32_bf16 v[10:13], v[180:183], v[212:215], v[10:13]
	v_mfma_f32_16x16x32_bf16 v[6:9], v[168:171], v[220:223], v[6:9]
	v_mfma_f32_16x16x32_bf16 v[6:9], v[172:175], v[224:227], v[6:9]
	v_mfma_f32_16x16x32_bf16 v[2:5], v[176:179], v[220:223], v[2:5]
	v_mfma_f32_16x16x32_bf16 v[2:5], v[180:183], v[224:227], v[2:5]
	s_barrier
	s_setprio 0
	s_add_i32 s50, s50, 2
	s_add_u32 s48, s48, 0x40000
	s_addc_u32 s49, s49, 0
	s_add_u32 s16, s16, 0x10000
	s_addc_u32 s17, s17, 0
	s_cmp_gt_u32 s50, 61
	s_cbranch_scc0 .LBB0_1718
	v_mov_b32_e32 v138, v146
	s_lshl_b32 s16, s45, 8
	v_and_or_b32 v152, v138, 15, s27
	v_lshrrev_b32_e32 v138, 1, v138
	v_and_or_b32 v138, v138, 24, s16
	v_ashrrev_i32_e32 v153, 31, v152
	v_or_b32_e32 v138, s28, v138
	v_lshlrev_b64 v[144:145], 11, v[152:153]
	v_lshl_add_u64 v[144:145], s[8:9], 0, v[144:145]
	v_lshlrev_b64 v[154:155], 1, v[138:139]
	v_lshl_add_u64 v[144:145], v[144:145], 0, v[154:155]
	v_cvt_pk_bf16_f32 v126, v126, v127
	v_cvt_pk_bf16_f32 v127, v128, v129
	v_cvt_pk_bf16_f32 v128, v122, v123
	v_cvt_pk_bf16_f32 v129, v124, v125
	global_store_dwordx4 v[144:145], v[126:129], off
	v_cvt_pk_bf16_f32 v114, v114, v115
	v_cvt_pk_bf16_f32 v115, v116, v117
	v_cvt_pk_bf16_f32 v116, v106, v107
	v_or_b32_e32 v106, 16, v152
	v_ashrrev_i32_e32 v107, 31, v106
	v_lshlrev_b64 v[106:107], 11, v[106:107]
	v_lshl_add_u64 v[106:107], s[8:9], 0, v[106:107]
	v_cvt_pk_bf16_f32 v117, v108, v109
	global_store_dwordx4 v[144:145], v[114:117], off offset:256
	s_mov_b64 s[16:17], 0x40000
	s_cmp_eq_u32 s44, 4
	v_lshl_add_u64 v[114:115], v[106:107], 0, v[154:155]
	v_cvt_pk_bf16_f32 v106, v118, v119
	v_cvt_pk_bf16_f32 v107, v120, v121
	v_cvt_pk_bf16_f32 v108, v110, v111
	v_cvt_pk_bf16_f32 v109, v112, v113
	global_store_dwordx4 v[114:115], v[106:109], off
	v_cvt_pk_bf16_f32 v98, v98, v99
	v_cvt_pk_bf16_f32 v99, v100, v101
	v_cvt_pk_bf16_f32 v100, v90, v91
	v_or_b32_e32 v90, 32, v152
	v_ashrrev_i32_e32 v91, 31, v90
	v_lshlrev_b64 v[90:91], 11, v[90:91]
	v_lshl_add_u64 v[90:91], s[8:9], 0, v[90:91]
	v_cvt_pk_bf16_f32 v101, v92, v93
	global_store_dwordx4 v[114:115], v[98:101], off offset:256
	s_mov_b32 s45, s44
	s_nop 0
	v_lshl_add_u64 v[98:99], v[90:91], 0, v[154:155]
	v_cvt_pk_bf16_f32 v90, v102, v103
	v_cvt_pk_bf16_f32 v91, v104, v105
	v_cvt_pk_bf16_f32 v92, v94, v95
	v_cvt_pk_bf16_f32 v93, v96, v97
	global_store_dwordx4 v[98:99], v[90:93], off
	v_cvt_pk_bf16_f32 v82, v82, v83
	v_cvt_pk_bf16_f32 v83, v84, v85
	v_cvt_pk_bf16_f32 v84, v74, v75
	v_or_b32_e32 v74, 48, v152
	v_ashrrev_i32_e32 v75, 31, v74
	v_lshlrev_b64 v[74:75], 11, v[74:75]
	v_lshl_add_u64 v[74:75], s[8:9], 0, v[74:75]
	v_cvt_pk_bf16_f32 v85, v76, v77
	global_store_dwordx4 v[98:99], v[82:85], off offset:256
	s_nop 1
	v_lshl_add_u64 v[82:83], v[74:75], 0, v[154:155]
	v_cvt_pk_bf16_f32 v74, v86, v87
	v_cvt_pk_bf16_f32 v75, v88, v89
	v_cvt_pk_bf16_f32 v76, v78, v79
	v_cvt_pk_bf16_f32 v77, v80, v81
	global_store_dwordx4 v[82:83], v[74:77], off
	v_cvt_pk_bf16_f32 v70, v70, v71
	v_cvt_pk_bf16_f32 v71, v72, v73
	v_cvt_pk_bf16_f32 v72, v66, v67
	v_lshl_add_u64 v[66:67], v[144:145], 0, s[16:17]
	s_mov_b32 s16, 0x40000
	v_cvt_pk_bf16_f32 v73, v68, v69
	global_store_dwordx4 v[82:83], v[70:73], off offset:256
	v_cvt_pk_bf16_f32 v62, v62, v63
	v_cvt_pk_bf16_f32 v63, v64, v65
	v_cvt_pk_bf16_f32 v64, v58, v59
	v_add_co_u32_e32 v58, vcc, s16, v144
	v_cvt_pk_bf16_f32 v65, v60, v61
	s_mov_b64 s[16:17], 0x48000
	s_nop 0
	v_addc_co_u32_e32 v59, vcc, 0, v145, vcc
	global_store_dwordx4 v[58:59], v[62:65], off
	v_cvt_pk_bf16_f32 v50, v50, v51
	v_cvt_pk_bf16_f32 v51, v52, v53
	v_cvt_pk_bf16_f32 v52, v42, v43
	v_cvt_pk_bf16_f32 v53, v44, v45
	global_store_dwordx4 v[66:67], v[50:53], off offset:256
	v_cvt_pk_bf16_f32 v42, v54, v55
	v_cvt_pk_bf16_f32 v43, v56, v57
	v_cvt_pk_bf16_f32 v44, v46, v47
	v_cvt_pk_bf16_f32 v45, v48, v49
	s_nop 1
	v_lshl_add_u64 v[50:51], v[144:145], 0, s[16:17]
	s_mov_b32 s16, 0x48000
	v_add_co_u32_e32 v46, vcc, s16, v144
	s_mov_b64 s[16:17], s[10:11]
	s_nop 0
	v_addc_co_u32_e32 v47, vcc, 0, v145, vcc
	global_store_dwordx4 v[46:47], v[42:45], off
	v_cvt_pk_bf16_f32 v34, v34, v35
	v_cvt_pk_bf16_f32 v35, v36, v37
	v_cvt_pk_bf16_f32 v36, v26, v27
	v_cvt_pk_bf16_f32 v37, v28, v29
	global_store_dwordx4 v[50:51], v[34:37], off offset:256
	v_cvt_pk_bf16_f32 v26, v38, v39
	v_cvt_pk_bf16_f32 v27, v40, v41
	v_cvt_pk_bf16_f32 v28, v30, v31
	v_add_co_u32_e32 v30, vcc, s34, v144
	s_nop 0
	v_lshl_add_u64 v[34:35], v[144:145], 0, s[4:5]
	v_addc_co_u32_e32 v31, vcc, 0, v145, vcc
	v_cvt_pk_bf16_f32 v29, v32, v33
	global_store_dwordx4 v[30:31], v[26:29], off
	v_cvt_pk_bf16_f32 v18, v18, v19
	v_cvt_pk_bf16_f32 v19, v20, v21
	v_cvt_pk_bf16_f32 v20, v10, v11
	v_cvt_pk_bf16_f32 v21, v12, v13
	global_store_dwordx4 v[34:35], v[18:21], off offset:256
	v_cvt_pk_bf16_f32 v10, v22, v23
	v_cvt_pk_bf16_f32 v11, v24, v25
	v_cvt_pk_bf16_f32 v12, v14, v15
	v_add_co_u32_e32 v14, vcc, s35, v144
	s_nop 0
	v_lshl_add_u64 v[18:19], v[144:145], 0, s[6:7]
	v_addc_co_u32_e32 v15, vcc, 0, v145, vcc
	v_cvt_pk_bf16_f32 v13, v16, v17
	global_store_dwordx4 v[14:15], v[10:13], off
	v_cvt_pk_bf16_f32 v6, v6, v7
	v_cvt_pk_bf16_f32 v7, v8, v9
	v_cvt_pk_bf16_f32 v8, v2, v3
	v_cvt_pk_bf16_f32 v9, v4, v5
	global_store_dwordx4 v[18:19], v[6:9], off offset:256
	s_cbranch_scc0 .LBB0_1717
	s_waitcnt vmcnt(0)
	s_cmpk_gt_u32 s0, 0xff
	s_cbranch_scc1 .LBB0_1722
	s_barrier

.LBB0_2185:
	ds_read_b128 v[146:149], v152
	ds_read_b128 v[156:159], v152 offset:1024
	ds_read_b128 v[160:163], v152 offset:2048
	ds_read_b128 v[164:167], v152 offset:3072
	ds_read_b128 v[168:171], v153
	ds_read_b128 v[172:175], v153 offset:1024
	ds_read_b128 v[176:179], v153 offset:2048
	ds_read_b128 v[180:183], v153 offset:3072
	s_add_u32 s22, s20, 0xfc000
	s_addc_u32 s23, s21, 0
	s_cmp_eq_u32 s44, 4
	s_cselect_b32 s26, s15, s22
	s_cselect_b32 s27, s5, s23
	s_cselect_b32 s24, s41, s42
	s_cselect_b32 s25, s13, s43
	s_add_u32 s22, s26, 0x100000
	s_addc_u32 s23, s27, 0
	s_add_i32 m0, s1, 0xc000
	ds_read_b128 v[184:187], v154
	ds_read_b128 v[188:191], v154 offset:1024
	ds_read_b128 v[192:195], v154 offset:2048
	ds_read_b128 v[196:199], v154 offset:3072
	ds_read_b128 v[206:209], v154 offset:4096
	ds_read_b128 v[212:215], v154 offset:5120
	ds_read_b128 v[220:223], v154 offset:6144
	ds_read_b128 v[224:227], v154 offset:7168
	global_load_lds_dwordx4 v138, s[20:21]
	s_add_i32 m0, s1, 0xe000
	s_nop 0
	global_load_lds_dwordx4 v140, s[20:21]
	s_waitcnt vmcnt(8)
	s_waitcnt lgkmcnt(0)
	s_setprio 1
	s_barrier
	v_mfma_f32_16x16x32_bf16 v[126:129], v[146:149], v[184:187], v[126:129]
	v_mfma_f32_16x16x32_bf16 v[126:129], v[156:159], v[188:191], v[126:129]
	v_mfma_f32_16x16x32_bf16 v[122:125], v[160:163], v[184:187], v[122:125]
	v_mfma_f32_16x16x32_bf16 v[122:125], v[164:167], v[188:191], v[122:125]
	v_mfma_f32_16x16x32_bf16 v[110:113], v[146:149], v[192:195], v[110:113]
	v_mfma_f32_16x16x32_bf16 v[110:113], v[156:159], v[196:199], v[110:113]
	v_mfma_f32_16x16x32_bf16 v[106:109], v[160:163], v[192:195], v[106:109]
	v_mfma_f32_16x16x32_bf16 v[106:109], v[164:167], v[196:199], v[106:109]
	v_mfma_f32_16x16x32_bf16 v[94:97], v[146:149], v[206:209], v[94:97]
	v_mfma_f32_16x16x32_bf16 v[94:97], v[156:159], v[212:215], v[94:97]
	v_mfma_f32_16x16x32_bf16 v[90:93], v[160:163], v[206:209], v[90:93]
	v_mfma_f32_16x16x32_bf16 v[90:93], v[164:167], v[212:215], v[90:93]
	v_mfma_f32_16x16x32_bf16 v[78:81], v[146:149], v[220:223], v[78:81]
	v_mfma_f32_16x16x32_bf16 v[78:81], v[156:159], v[224:227], v[78:81]
	v_mfma_f32_16x16x32_bf16 v[74:77], v[160:163], v[220:223], v[74:77]
	v_mfma_f32_16x16x32_bf16 v[74:77], v[164:167], v[224:227], v[74:77]
	s_setprio 0
	s_setprio 1
	v_mfma_f32_16x16x32_bf16 v[118:121], v[168:171], v[184:187], v[118:121]
	v_mfma_f32_16x16x32_bf16 v[118:121], v[172:175], v[188:191], v[118:121]
	v_mfma_f32_16x16x32_bf16 v[114:117], v[176:179], v[184:187], v[114:117]
	v_mfma_f32_16x16x32_bf16 v[114:117], v[180:183], v[188:191], v[114:117]
	v_mfma_f32_16x16x32_bf16 v[102:105], v[168:171], v[192:195], v[102:105]
	v_mfma_f32_16x16x32_bf16 v[102:105], v[172:175], v[196:199], v[102:105]
	v_mfma_f32_16x16x32_bf16 v[98:101], v[176:179], v[192:195], v[98:101]
	v_mfma_f32_16x16x32_bf16 v[98:101], v[180:183], v[196:199], v[98:101]
	v_mfma_f32_16x16x32_bf16 v[86:89], v[168:171], v[206:209], v[86:89]
	v_mfma_f32_16x16x32_bf16 v[86:89], v[172:175], v[212:215], v[86:89]
	v_mfma_f32_16x16x32_bf16 v[82:85], v[176:179], v[206:209], v[82:85]
	v_mfma_f32_16x16x32_bf16 v[82:85], v[180:183], v[212:215], v[82:85]
	v_mfma_f32_16x16x32_bf16 v[70:73], v[168:171], v[220:223], v[70:73]
	v_mfma_f32_16x16x32_bf16 v[70:73], v[172:175], v[224:227], v[70:73]
	v_mfma_f32_16x16x32_bf16 v[66:69], v[176:179], v[220:223], v[66:69]
	v_mfma_f32_16x16x32_bf16 v[66:69], v[180:183], v[224:227], v[66:69]
	s_barrier
	s_setprio 0
	s_add_i32 s45, s38, s0
	s_mov_b32 m0, s45
	ds_read_b128 v[184:187], v154 offset:16384
	ds_read_b128 v[188:191], v154 offset:17408
	ds_read_b128 v[192:195], v154 offset:18432
	ds_read_b128 v[196:199], v154 offset:19456
	ds_read_b128 v[206:209], v154 offset:20480
	ds_read_b128 v[212:215], v154 offset:21504
	ds_read_b128 v[220:223], v154 offset:22528
	ds_read_b128 v[224:227], v154 offset:23552
	global_load_lds_dwordx4 v132, s[24:25]
	s_add_i32 m0, s45, 0x2000
	s_add_u32 s46, s24, 0x4000
	s_addc_u32 s47, s25, 0
	s_add_i32 s45, s39, s0
	global_load_lds_dwordx4 v136, s[24:25]
	s_mov_b32 m0, s45
	s_nop 0
	global_load_lds_dwordx4 v132, s[46:47]
	s_add_i32 m0, s45, 0x2000
	s_nop 0
	global_load_lds_dwordx4 v136, s[46:47]
	s_mov_b32 m0, s1
	s_nop 0
	global_load_lds_dwordx4 v130, s[26:27]
	s_mov_b32 m0, s28
	s_nop 0
	global_load_lds_dwordx4 v134, s[26:27]
	s_waitcnt vmcnt(8)
	s_waitcnt lgkmcnt(0)
	s_setprio 1
	s_barrier
	v_mfma_f32_16x16x32_bf16 v[62:65], v[146:149], v[184:187], v[62:65]
	v_mfma_f32_16x16x32_bf16 v[62:65], v[156:159], v[188:191], v[62:65]
	v_mfma_f32_16x16x32_bf16 v[58:61], v[160:163], v[184:187], v[58:61]
	v_mfma_f32_16x16x32_bf16 v[58:61], v[164:167], v[188:191], v[58:61]
	v_mfma_f32_16x16x32_bf16 v[46:49], v[146:149], v[192:195], v[46:49]
	v_mfma_f32_16x16x32_bf16 v[46:49], v[156:159], v[196:199], v[46:49]
	v_mfma_f32_16x16x32_bf16 v[42:45], v[160:163], v[192:195], v[42:45]
	v_mfma_f32_16x16x32_bf16 v[42:45], v[164:167], v[196:199], v[42:45]
	v_mfma_f32_16x16x32_bf16 v[30:33], v[146:149], v[206:209], v[30:33]
	v_mfma_f32_16x16x32_bf16 v[30:33], v[156:159], v[212:215], v[30:33]
	v_mfma_f32_16x16x32_bf16 v[26:29], v[160:163], v[206:209], v[26:29]
	v_mfma_f32_16x16x32_bf16 v[26:29], v[164:167], v[212:215], v[26:29]
	v_mfma_f32_16x16x32_bf16 v[14:17], v[146:149], v[220:223], v[14:17]
	v_mfma_f32_16x16x32_bf16 v[14:17], v[156:159], v[224:227], v[14:17]
	v_mfma_f32_16x16x32_bf16 v[10:13], v[160:163], v[220:223], v[10:13]
	v_mfma_f32_16x16x32_bf16 v[10:13], v[164:167], v[224:227], v[10:13]
	s_setprio 0
	s_setprio 1
	v_mfma_f32_16x16x32_bf16 v[54:57], v[168:171], v[184:187], v[54:57]
	v_mfma_f32_16x16x32_bf16 v[54:57], v[172:175], v[188:191], v[54:57]
	v_mfma_f32_16x16x32_bf16 v[50:53], v[176:179], v[184:187], v[50:53]
	v_mfma_f32_16x16x32_bf16 v[50:53], v[180:183], v[188:191], v[50:53]
	v_mfma_f32_16x16x32_bf16 v[38:41], v[168:171], v[192:195], v[38:41]
	v_mfma_f32_16x16x32_bf16 v[38:41], v[172:175], v[196:199], v[38:41]
	v_mfma_f32_16x16x32_bf16 v[34:37], v[176:179], v[192:195], v[34:37]
	v_mfma_f32_16x16x32_bf16 v[34:37], v[180:183], v[196:199], v[34:37]
	v_mfma_f32_16x16x32_bf16 v[22:25], v[168:171], v[206:209], v[22:25]
	v_mfma_f32_16x16x32_bf16 v[22:25], v[172:175], v[212:215], v[22:25]
	v_mfma_f32_16x16x32_bf16 v[18:21], v[176:179], v[206:209], v[18:21]
	v_mfma_f32_16x16x32_bf16 v[18:21], v[180:183], v[212:215], v[18:21]
	v_mfma_f32_16x16x32_bf16 v[6:9], v[168:171], v[220:223], v[6:9]
	v_mfma_f32_16x16x32_bf16 v[6:9], v[172:175], v[224:227], v[6:9]
	v_mfma_f32_16x16x32_bf16 v[2:5], v[176:179], v[220:223], v[2:5]
	v_mfma_f32_16x16x32_bf16 v[2:5], v[180:183], v[224:227], v[2:5]
	s_barrier
	s_setprio 0
	s_add_i32 s45, 0, 0x18000
	v_add_u32_e32 v155, s45, v151
	s_add_i32 s46, 0, 0x1c000
	ds_read_b128 v[146:149], v155
	ds_read_b128 v[156:159], v155 offset:1024
	ds_read_b128 v[160:163], v155 offset:2048
	ds_read_b128 v[164:167], v155 offset:3072
	v_add_u32_e32 v155, s46, v151
	ds_read_b128 v[168:171], v155
	ds_read_b128 v[172:175], v155 offset:1024
	ds_read_b128 v[176:179], v155 offset:2048
	ds_read_b128 v[180:183], v155 offset:3072
	s_add_u32 s26, s26, 0x4000
	s_addc_u32 s27, s27, 0
	s_mov_b32 m0, s29
	ds_read_b128 v[184:187], v154 offset:32768
	ds_read_b128 v[188:191], v154 offset:33792
	ds_read_b128 v[192:195], v154 offset:34816
	ds_read_b128 v[196:199], v154 offset:35840
	ds_read_b128 v[206:209], v154 offset:36864
	ds_read_b128 v[212:215], v154 offset:37888
	ds_read_b128 v[220:223], v154 offset:38912
	ds_read_b128 v[224:227], v154 offset:39936
	global_load_lds_dwordx4 v130, s[26:27]
	s_mov_b32 m0, s30
	s_nop 0
	global_load_lds_dwordx4 v134, s[26:27]
	s_waitcnt vmcnt(8)
	s_waitcnt lgkmcnt(0)
	s_setprio 1
	s_barrier
	v_mfma_f32_16x16x32_bf16 v[126:129], v[146:149], v[184:187], v[126:129]
	v_mfma_f32_16x16x32_bf16 v[126:129], v[156:159], v[188:191], v[126:129]
	v_mfma_f32_16x16x32_bf16 v[122:125], v[160:163], v[184:187], v[122:125]
	v_mfma_f32_16x16x32_bf16 v[122:125], v[164:167], v[188:191], v[122:125]
	v_mfma_f32_16x16x32_bf16 v[110:113], v[146:149], v[192:195], v[110:113]
	v_mfma_f32_16x16x32_bf16 v[110:113], v[156:159], v[196:199], v[110:113]
	v_mfma_f32_16x16x32_bf16 v[106:109], v[160:163], v[192:195], v[106:109]
	v_mfma_f32_16x16x32_bf16 v[106:109], v[164:167], v[196:199], v[106:109]
	v_mfma_f32_16x16x32_bf16 v[94:97], v[146:149], v[206:209], v[94:97]
	v_mfma_f32_16x16x32_bf16 v[94:97], v[156:159], v[212:215], v[94:97]
	v_mfma_f32_16x16x32_bf16 v[90:93], v[160:163], v[206:209], v[90:93]
	v_mfma_f32_16x16x32_bf16 v[90:93], v[164:167], v[212:215], v[90:93]
	v_mfma_f32_16x16x32_bf16 v[78:81], v[146:149], v[220:223], v[78:81]
	v_mfma_f32_16x16x32_bf16 v[78:81], v[156:159], v[224:227], v[78:81]
	v_mfma_f32_16x16x32_bf16 v[74:77], v[160:163], v[220:223], v[74:77]
	v_mfma_f32_16x16x32_bf16 v[74:77], v[164:167], v[224:227], v[74:77]
	s_setprio 0
	s_setprio 1
	v_mfma_f32_16x16x32_bf16 v[118:121], v[168:171], v[184:187], v[118:121]
	v_mfma_f32_16x16x32_bf16 v[118:121], v[172:175], v[188:191], v[118:121]
	v_mfma_f32_16x16x32_bf16 v[114:117], v[176:179], v[184:187], v[114:117]
	v_mfma_f32_16x16x32_bf16 v[114:117], v[180:183], v[188:191], v[114:117]
	v_mfma_f32_16x16x32_bf16 v[102:105], v[168:171], v[192:195], v[102:105]
	v_mfma_f32_16x16x32_bf16 v[102:105], v[172:175], v[196:199], v[102:105]
	v_mfma_f32_16x16x32_bf16 v[98:101], v[176:179], v[192:195], v[98:101]
	v_mfma_f32_16x16x32_bf16 v[98:101], v[180:183], v[196:199], v[98:101]
	v_mfma_f32_16x16x32_bf16 v[86:89], v[168:171], v[206:209], v[86:89]
	v_mfma_f32_16x16x32_bf16 v[86:89], v[172:175], v[212:215], v[86:89]
	v_mfma_f32_16x16x32_bf16 v[82:85], v[176:179], v[206:209], v[82:85]
	v_mfma_f32_16x16x32_bf16 v[82:85], v[180:183], v[212:215], v[82:85]
	v_mfma_f32_16x16x32_bf16 v[70:73], v[168:171], v[220:223], v[70:73]
	v_mfma_f32_16x16x32_bf16 v[70:73], v[172:175], v[224:227], v[70:73]
	v_mfma_f32_16x16x32_bf16 v[66:69], v[176:179], v[220:223], v[66:69]
	v_mfma_f32_16x16x32_bf16 v[66:69], v[180:183], v[224:227], v[66:69]
	s_barrier
	s_setprio 0
	s_add_u32 s26, s24, 0x80000
	s_addc_u32 s27, s25, 0
	s_add_i32 s45, s45, s0
	s_mov_b32 m0, s45
	ds_read_b128 v[184:187], v154 offset:49152
	ds_read_b128 v[188:191], v154 offset:50176
	ds_read_b128 v[192:195], v154 offset:51200
	ds_read_b128 v[196:199], v154 offset:52224
	ds_read_b128 v[206:209], v154 offset:53248
	ds_read_b128 v[212:215], v154 offset:54272
	ds_read_b128 v[220:223], v154 offset:55296
	ds_read_b128 v[224:227], v154 offset:56320
	global_load_lds_dwordx4 v132, s[26:27]
	s_add_i32 m0, s45, 0x2000
	s_add_u32 s24, s24, 0x84000
	s_addc_u32 s25, s25, 0
	global_load_lds_dwordx4 v136, s[26:27]
	s_add_i32 s26, s46, s0
	s_mov_b32 m0, s26
	s_nop 0
	global_load_lds_dwordx4 v132, s[24:25]
	s_add_i32 m0, s26, 0x2000
	s_nop 0
	global_load_lds_dwordx4 v136, s[24:25]
	s_mov_b32 m0, s36
	s_nop 0
	global_load_lds_dwordx4 v130, s[22:23]
	s_mov_b32 m0, s37
	s_nop 0
	global_load_lds_dwordx4 v134, s[22:23]
	s_waitcnt vmcnt(8)
	s_waitcnt lgkmcnt(0)
	s_setprio 1
	s_barrier
	v_mfma_f32_16x16x32_bf16 v[62:65], v[146:149], v[184:187], v[62:65]
	v_mfma_f32_16x16x32_bf16 v[62:65], v[156:159], v[188:191], v[62:65]
	v_mfma_f32_16x16x32_bf16 v[58:61], v[160:163], v[184:187], v[58:61]
	v_mfma_f32_16x16x32_bf16 v[58:61], v[164:167], v[188:191], v[58:61]
	v_mfma_f32_16x16x32_bf16 v[46:49], v[146:149], v[192:195], v[46:49]
	v_mfma_f32_16x16x32_bf16 v[46:49], v[156:159], v[196:199], v[46:49]
	v_mfma_f32_16x16x32_bf16 v[42:45], v[160:163], v[192:195], v[42:45]
	v_mfma_f32_16x16x32_bf16 v[42:45], v[164:167], v[196:199], v[42:45]
	v_mfma_f32_16x16x32_bf16 v[30:33], v[146:149], v[206:209], v[30:33]
	v_mfma_f32_16x16x32_bf16 v[30:33], v[156:159], v[212:215], v[30:33]
	v_mfma_f32_16x16x32_bf16 v[26:29], v[160:163], v[206:209], v[26:29]
	v_mfma_f32_16x16x32_bf16 v[26:29], v[164:167], v[212:215], v[26:29]
	v_mfma_f32_16x16x32_bf16 v[14:17], v[146:149], v[220:223], v[14:17]
	v_mfma_f32_16x16x32_bf16 v[14:17], v[156:159], v[224:227], v[14:17]
	v_mfma_f32_16x16x32_bf16 v[10:13], v[160:163], v[220:223], v[10:13]
	v_mfma_f32_16x16x32_bf16 v[10:13], v[164:167], v[224:227], v[10:13]
	s_setprio 0
	s_setprio 1
	v_mfma_f32_16x16x32_bf16 v[54:57], v[168:171], v[184:187], v[54:57]
	v_mfma_f32_16x16x32_bf16 v[54:57], v[172:175], v[188:191], v[54:57]
	v_mfma_f32_16x16x32_bf16 v[50:53], v[176:179], v[184:187], v[50:53]
	v_mfma_f32_16x16x32_bf16 v[50:53], v[180:183], v[188:191], v[50:53]
	v_mfma_f32_16x16x32_bf16 v[38:41], v[168:171], v[192:195], v[38:41]
	v_mfma_f32_16x16x32_bf16 v[38:41], v[172:175], v[196:199], v[38:41]
	v_mfma_f32_16x16x32_bf16 v[34:37], v[176:179], v[192:195], v[34:37]
	v_mfma_f32_16x16x32_bf16 v[34:37], v[180:183], v[196:199], v[34:37]
	v_mfma_f32_16x16x32_bf16 v[22:25], v[168:171], v[206:209], v[22:25]
	v_mfma_f32_16x16x32_bf16 v[22:25], v[172:175], v[212:215], v[22:25]
	v_mfma_f32_16x16x32_bf16 v[18:21], v[176:179], v[206:209], v[18:21]
	v_mfma_f32_16x16x32_bf16 v[18:21], v[180:183], v[212:215], v[18:21]
	v_mfma_f32_16x16x32_bf16 v[6:9], v[168:171], v[220:223], v[6:9]
	v_mfma_f32_16x16x32_bf16 v[6:9], v[172:175], v[224:227], v[6:9]
	v_mfma_f32_16x16x32_bf16 v[2:5], v[176:179], v[220:223], v[2:5]
	v_mfma_f32_16x16x32_bf16 v[2:5], v[180:183], v[224:227], v[2:5]
	s_barrier
	s_setprio 0
	s_add_i32 s44, s44, 2
	s_add_u32 s42, s42, 0x100000
	s_addc_u32 s43, s43, 0
	s_add_u32 s20, s20, 0x200000
	s_addc_u32 s21, s21, 0
	s_cmp_gt_u32 s44, 5
	s_cbranch_scc0 .LBB0_2185
	s_and_b64 vcc, exec, s[8:9]
	s_cbranch_vccz .LBB0_2188
	s_barrier
